# p4: mid-K gate hook de-serialized - extra barrier pair so both wave groups run the hook concurrently
# speedup vs baseline: 1.0102x; 1.0095x over previous
; DI float lo16(unsigned u) { return __uint_as_float(u << 16); }
; DI float hi16(unsigned u) { return __uint_as_float(u & 0xffff0000u); }
; DI int opaque_i(int v) { asm volatile("" : "+v"(v)); return v; }
; template <class Epi>
; DI void gemm_phase(LAS unsigned char* lds, const Gemm g, const StaticOrder& S, const Epi& E) {
;     ...
;             if constexpr (Epi::HAS_MID) { if (t == Epi::MID_T) E.mid(acc, cur, wr, wc, fr, fq); }
;     DI void mid(f32x4 (&acc)[2][2][4][2], const Unit& u, int wr, int wc, int fr, int fq) const {
;         const int row0 = opaque_i(u.pm * BM + wr * 64 + fr), col0 = opaque_i(u.pn * BM + wc * 32 + 8 * fq);
; #pragma unroll
;         for (int ai = 0; ai < 2; ++ai) {
;             u32x4 gs[4][2], gn[4][2]; float rs[4];
; #pragma unroll
;             for (int m = 0; m < 4; ++m) { const int row = row0 + ai * HALF + m * 16; const bf16_t* rowp = P + (size_t)row * LDP + col0; rs[m] = rstd[row];
; #pragma unroll
;                 for (int bj = 0; bj < 2; ++bj) { gs[m][bj] = *(const u32x4*)(rowp + bj * HALF + C_GLS); gn[m][bj] = *(const u32x4*)(rowp + bj * HALF + C_GLN); } }
; #pragma unroll
;             for (int m = 0; m < 4; ++m)
; #pragma unroll
;                 for (int bj = 0; bj < 2; ++bj) {
;                     const unsigned gsw[4] = {gs[m][bj].x, gs[m][bj].y, gs[m][bj].z, gs[m][bj].w}, gnw[4] = {gn[m][bj].x, gn[m][bj].y, gn[m][bj].z, gn[m][bj].w};
; #pragma unroll
;                     for (int j = 0; j < 4; ++j) {
;                         const float r0 = rs[m] * (1.f + __expf(-lo16(gnw[j]))) * __builtin_amdgcn_rcpf(1.f + __expf(-lo16(gsw[j])));
;                         const float r1 = rs[m] * (1.f + __expf(-hi16(gnw[j]))) * __builtin_amdgcn_rcpf(1.f + __expf(-hi16(gsw[j])));
;                         acc[ai][bj][m][j >> 1][(j & 1) * 2] *= r0; acc[ai][bj][m][j >> 1][(j & 1) * 2 + 1] *= r1; } }
.LBB0_631:
	s_cmpk_lg_i32 s36, 0x1000
	s_cbranch_scc1 .LBB0_630
	s_cmpk_gt_u32 s42, 0xff
	s_cbranch_scc1 .Lhook_e0
	s_barrier
.Lhook_e0:
	v_mov_b32_e32 v2, v223
	v_mov_b32_e32 v132, v204
	s_nop 0
	v_ashrrev_i32_e32 v133, 31, v132
	v_lshl_add_u64 v[210:211], v[132:133], 1, s[30:31]
	v_mad_i64_i32 v[132:133], s[0:1], v2, s54, v[210:211]
	v_add_co_u32_e32 v134, vcc, 0x5000, v132
	v_ashrrev_i32_e32 v3, 31, v2
	s_nop 0
	v_addc_co_u32_e32 v135, vcc, 0, v133, vcc
	global_load_dwordx4 v[224:227], v[134:135], off offset:1024
	v_add_co_u32_e32 v132, vcc, s49, v132
	v_lshl_add_u64 v[212:213], v[2:3], 2, s[8:9]
	s_nop 0
	v_addc_co_u32_e32 v133, vcc, 0, v133, vcc
	global_load_dwordx4 v[228:231], v[132:133], off offset:1024
	global_load_dword v220, v[212:213], off
	global_load_dword v218, v[212:213], off offset:64
	global_load_dword v216, v[212:213], off offset:128
	global_load_dword v214, v[212:213], off offset:192
	global_load_dwordx4 v[184:187], v[134:135], off offset:1280
	global_load_dwordx4 v[180:183], v[132:133], off offset:1280
	v_add_u32_e32 v1, 16, v2
	v_mad_i64_i32 v[136:137], s[0:1], v1, s54, v[210:211]
	v_add_co_u32_e32 v134, vcc, s55, v136
	v_add_u32_e32 v138, 32, v2
	s_nop 0
	v_addc_co_u32_e32 v135, vcc, 0, v137, vcc
	global_load_dwordx4 v[172:175], v[134:135], off offset:1024
	global_load_dwordx4 v[164:167], v[134:135], off offset:1280
	v_add_co_u32_e32 v132, vcc, s49, v136
	v_mad_i64_i32 v[138:139], s[0:1], v138, s54, v[210:211]
	s_nop 0
	v_addc_co_u32_e32 v133, vcc, 0, v137, vcc
	global_load_dwordx4 v[176:179], v[132:133], off offset:1024
	global_load_dwordx4 v[168:171], v[132:133], off offset:1280
	v_add_co_u32_e32 v134, vcc, s55, v138
	v_add_u32_e32 v140, 48, v2
	s_nop 0
	v_addc_co_u32_e32 v135, vcc, 0, v139, vcc
	global_load_dwordx4 v[156:159], v[134:135], off offset:1024
	global_load_dwordx4 v[148:151], v[134:135], off offset:1280
	v_add_co_u32_e32 v132, vcc, s49, v138
	v_mad_i64_i32 v[140:141], s[0:1], v140, s54, v[210:211]
	s_nop 0
	v_addc_co_u32_e32 v133, vcc, 0, v139, vcc
	global_load_dwordx4 v[160:163], v[132:133], off offset:1024
	global_load_dwordx4 v[152:155], v[132:133], off offset:1280
	v_add_co_u32_e32 v134, vcc, s55, v140
	s_waitcnt vmcnt(0)
	v_lshlrev_b32_e32 v1, 16, v224
	v_mul_f32_e32 v1, 0xbfb8aa3b, v1
	v_exp_f32_e32 v1, v1
	v_and_b32_e32 v3, 0xffff0000, v224
	v_mul_f32_e32 v3, 0xbfb8aa3b, v3
	v_exp_f32_e32 v3, v3
	v_add_f32_e32 v1, 1.0, v1
	v_rcp_f32_e32 v234, v1
	v_lshlrev_b32_e32 v1, 16, v225
	v_mul_f32_e32 v1, 0xbfb8aa3b, v1
	v_exp_f32_e32 v1, v1
	v_lshlrev_b32_e32 v205, 16, v228
	v_and_b32_e32 v224, 0xffff0000, v228
	v_add_f32_e32 v3, 1.0, v3
	v_add_f32_e32 v1, 1.0, v1
	v_rcp_f32_e32 v228, v1
	v_and_b32_e32 v1, 0xffff0000, v225
	v_mul_f32_e32 v1, 0xbfb8aa3b, v1
	v_exp_f32_e32 v1, v1
	v_rcp_f32_e32 v235, v3
	v_lshlrev_b32_e32 v3, 16, v229
	v_mul_f32_e32 v224, 0xbfb8aa3b, v224
	v_mul_f32_e32 v3, 0xbfb8aa3b, v3
	v_exp_f32_e32 v233, v224
	v_exp_f32_e32 v224, v3
	v_and_b32_e32 v3, 0xffff0000, v229
	v_add_f32_e32 v1, 1.0, v1
	v_mul_f32_e32 v3, 0xbfb8aa3b, v3
	v_rcp_f32_e32 v229, v1
	v_lshlrev_b32_e32 v1, 16, v226
	v_exp_f32_e32 v225, v3
	v_mul_f32_e32 v1, 0xbfb8aa3b, v1
	v_exp_f32_e32 v1, v1
	v_lshlrev_b32_e32 v3, 16, v230
	v_pk_add_f32 v[224:225], v[224:225], 1.0 op_sel_hi:[1,0]
	v_mul_f32_e32 v3, 0xbfb8aa3b, v3
	v_pk_mul_f32 v[224:225], v[220:221], v[224:225] op_sel_hi:[0,1]
	v_add_f32_e32 v1, 1.0, v1
	v_pk_mul_f32 v[224:225], v[228:229], v[224:225]
	v_rcp_f32_e32 v228, v1
	v_and_b32_e32 v1, 0xffff0000, v226
	v_mul_f32_e32 v1, 0xbfb8aa3b, v1
	v_exp_f32_e32 v1, v1
	v_pk_mul_f32 v[130:131], v[130:131], v[224:225]
	v_exp_f32_e32 v224, v3
	v_and_b32_e32 v3, 0xffff0000, v230
	v_add_f32_e32 v1, 1.0, v1
	v_rcp_f32_e32 v229, v1
	v_lshlrev_b32_e32 v1, 16, v227
	v_mul_f32_e32 v1, 0xbfb8aa3b, v1
	v_exp_f32_e32 v1, v1
	v_mul_f32_e32 v3, 0xbfb8aa3b, v3
	v_exp_f32_e32 v225, v3
	v_lshlrev_b32_e32 v3, 16, v231
	v_add_f32_e32 v1, 1.0, v1
	v_rcp_f32_e32 v230, v1
	v_and_b32_e32 v1, 0xffff0000, v227
	v_mul_f32_e32 v1, 0xbfb8aa3b, v1
	v_exp_f32_e32 v1, v1
	v_mul_f32_e32 v3, 0xbfb8aa3b, v3
	v_exp_f32_e32 v226, v3
	v_and_b32_e32 v3, 0xffff0000, v231
	v_mul_f32_e32 v3, 0xbfb8aa3b, v3
	v_add_f32_e32 v1, 1.0, v1
	v_exp_f32_e32 v227, v3
	v_rcp_f32_e32 v231, v1
	v_lshlrev_b32_e32 v1, 16, v184
	v_mul_f32_e32 v1, 0xbfb8aa3b, v1
	v_exp_f32_e32 v1, v1
	v_pk_add_f32 v[226:227], v[226:227], 1.0 op_sel_hi:[1,0]
	v_pk_add_f32 v[224:225], v[224:225], 1.0 op_sel_hi:[1,0]
	v_pk_mul_f32 v[226:227], v[220:221], v[226:227] op_sel_hi:[0,1]
	v_pk_mul_f32 v[226:227], v[230:231], v[226:227]
	v_add_f32_e32 v1, 1.0, v1
	v_pk_mul_f32 v[126:127], v[126:127], v[226:227]
	v_rcp_f32_e32 v226, v1
	v_and_b32_e32 v1, 0xffff0000, v184
	v_mul_f32_e32 v1, 0xbfb8aa3b, v1
	v_exp_f32_e32 v1, v1
	v_pk_mul_f32 v[224:225], v[220:221], v[224:225] op_sel_hi:[0,1]
	v_lshlrev_b32_e32 v3, 16, v180
	v_pk_mul_f32 v[224:225], v[228:229], v[224:225]
	v_add_f32_e32 v1, 1.0, v1
	v_rcp_f32_e32 v227, v1
	v_lshlrev_b32_e32 v1, 16, v185
	v_mul_f32_e32 v1, 0xbfb8aa3b, v1
	v_exp_f32_e32 v1, v1
	v_mul_f32_e32 v3, 0xbfb8aa3b, v3
	v_pk_mul_f32 v[124:125], v[124:125], v[224:225]
	v_exp_f32_e32 v224, v3
	v_add_f32_e32 v1, 1.0, v1
	v_rcp_f32_e32 v184, v1
	v_and_b32_e32 v1, 0xffff0000, v185
	v_mul_f32_e32 v1, 0xbfb8aa3b, v1
	v_and_b32_e32 v3, 0xffff0000, v180
	v_exp_f32_e32 v1, v1
	v_mul_f32_e32 v3, 0xbfb8aa3b, v3
	v_exp_f32_e32 v225, v3
	v_lshlrev_b32_e32 v3, 16, v181
	v_mul_f32_e32 v3, 0xbfb8aa3b, v3
	v_exp_f32_e32 v180, v3
	v_and_b32_e32 v3, 0xffff0000, v181
	v_add_f32_e32 v1, 1.0, v1
	v_mul_f32_e32 v3, 0xbfb8aa3b, v3
	v_rcp_f32_e32 v185, v1
	v_lshlrev_b32_e32 v1, 16, v186
	v_exp_f32_e32 v181, v3
; DI float lo16(unsigned u) { return __uint_as_float(u << 16); }
; DI float hi16(unsigned u) { return __uint_as_float(u & 0xffff0000u); }
;     DI void mid(f32x4 (&acc)[2][2][4][2], const Unit& u, int wr, int wc, int fr, int fq) const {
;     ...
;             for (int m = 0; m < 4; ++m)
; #pragma unroll
;                 for (int bj = 0; bj < 2; ++bj) {
;                     const unsigned gsw[4] = {gs[m][bj].x, gs[m][bj].y, gs[m][bj].z, gs[m][bj].w}, gnw[4] = {gn[m][bj].x, gn[m][bj].y, gn[m][bj].z, gn[m][bj].w};
; #pragma unroll
;                     for (int j = 0; j < 4; ++j) {
;                         const float r0 = rs[m] * (1.f + __expf(-lo16(gnw[j]))) * __builtin_amdgcn_rcpf(1.f + __expf(-lo16(gsw[j])));
;                         const float r1 = rs[m] * (1.f + __expf(-hi16(gnw[j]))) * __builtin_amdgcn_rcpf(1.f + __expf(-hi16(gsw[j])));
;                         acc[ai][bj][m][j >> 1][(j & 1) * 2] *= r0; acc[ai][bj][m][j >> 1][(j & 1) * 2 + 1] *= r1; } }
	v_mul_f32_e32 v1, 0xbfb8aa3b, v1
	v_exp_f32_e32 v1, v1
	v_lshlrev_b32_e32 v3, 16, v182
	v_pk_add_f32 v[180:181], v[180:181], 1.0 op_sel_hi:[1,0]
	v_mul_f32_e32 v3, 0xbfb8aa3b, v3
	v_pk_mul_f32 v[180:181], v[220:221], v[180:181] op_sel_hi:[0,1]
	v_add_f32_e32 v1, 1.0, v1
	v_pk_mul_f32 v[180:181], v[184:185], v[180:181]
	v_rcp_f32_e32 v184, v1
	v_and_b32_e32 v1, 0xffff0000, v186
	v_mul_f32_e32 v1, 0xbfb8aa3b, v1
	v_exp_f32_e32 v1, v1
	v_pk_mul_f32 v[122:123], v[122:123], v[180:181]
	v_exp_f32_e32 v180, v3
	v_and_b32_e32 v3, 0xffff0000, v182
	v_add_f32_e32 v1, 1.0, v1
	v_rcp_f32_e32 v185, v1
	v_lshlrev_b32_e32 v1, 16, v187
	v_mul_f32_e32 v1, 0xbfb8aa3b, v1
	v_exp_f32_e32 v1, v1
	v_mul_f32_e32 v3, 0xbfb8aa3b, v3
	v_exp_f32_e32 v181, v3
	v_lshlrev_b32_e32 v3, 16, v183
	v_add_f32_e32 v1, 1.0, v1
	v_rcp_f32_e32 v186, v1
	v_and_b32_e32 v1, 0xffff0000, v187
	v_mul_f32_e32 v1, 0xbfb8aa3b, v1
	v_exp_f32_e32 v1, v1
	v_mul_f32_e32 v3, 0xbfb8aa3b, v3
	v_exp_f32_e32 v182, v3
	v_and_b32_e32 v3, 0xffff0000, v183
	v_mul_f32_e32 v3, 0xbfb8aa3b, v3
	v_add_f32_e32 v1, 1.0, v1
	v_exp_f32_e32 v183, v3
	v_rcp_f32_e32 v187, v1
	v_lshlrev_b32_e32 v1, 16, v172
	v_mul_f32_e32 v1, 0xbfb8aa3b, v1
	v_exp_f32_e32 v1, v1
	v_pk_add_f32 v[182:183], v[182:183], 1.0 op_sel_hi:[1,0]
	v_pk_add_f32 v[180:181], v[180:181], 1.0 op_sel_hi:[1,0]
	v_pk_mul_f32 v[182:183], v[220:221], v[182:183] op_sel_hi:[0,1]
	v_pk_mul_f32 v[182:183], v[186:187], v[182:183]
	v_add_f32_e32 v1, 1.0, v1
	v_pk_mul_f32 v[118:119], v[118:119], v[182:183]
	v_rcp_f32_e32 v182, v1
	v_and_b32_e32 v1, 0xffff0000, v172
	v_mul_f32_e32 v1, 0xbfb8aa3b, v1
	v_exp_f32_e32 v1, v1
	v_pk_mul_f32 v[180:181], v[220:221], v[180:181] op_sel_hi:[0,1]
	v_lshlrev_b32_e32 v3, 16, v176
	v_pk_mul_f32 v[180:181], v[184:185], v[180:181]
	v_add_f32_e32 v1, 1.0, v1
	v_rcp_f32_e32 v183, v1
	v_lshlrev_b32_e32 v1, 16, v173
	v_mul_f32_e32 v1, 0xbfb8aa3b, v1
	v_exp_f32_e32 v1, v1
	v_mul_f32_e32 v3, 0xbfb8aa3b, v3
	v_pk_mul_f32 v[116:117], v[116:117], v[180:181]
	v_exp_f32_e32 v180, v3
	v_add_f32_e32 v1, 1.0, v1
	v_and_b32_e32 v3, 0xffff0000, v176
	v_rcp_f32_e32 v176, v1
	v_and_b32_e32 v1, 0xffff0000, v173
	v_mul_f32_e32 v1, 0xbfb8aa3b, v1
	v_exp_f32_e32 v1, v1
	v_mul_f32_e32 v3, 0xbfb8aa3b, v3
	v_exp_f32_e32 v181, v3
	v_lshlrev_b32_e32 v3, 16, v177
	v_mul_f32_e32 v3, 0xbfb8aa3b, v3
	v_exp_f32_e32 v172, v3
	v_and_b32_e32 v3, 0xffff0000, v177
	v_add_f32_e32 v1, 1.0, v1
	v_mul_f32_e32 v3, 0xbfb8aa3b, v3
	v_rcp_f32_e32 v177, v1
	v_lshlrev_b32_e32 v1, 16, v174
	v_exp_f32_e32 v173, v3
	v_mul_f32_e32 v1, 0xbfb8aa3b, v1
	v_exp_f32_e32 v1, v1
	v_lshlrev_b32_e32 v3, 16, v178
	v_pk_add_f32 v[172:173], v[172:173], 1.0 op_sel_hi:[1,0]
	v_mul_f32_e32 v3, 0xbfb8aa3b, v3
	v_pk_mul_f32 v[172:173], v[218:219], v[172:173] op_sel_hi:[0,1]
	v_add_f32_e32 v1, 1.0, v1
	v_pk_mul_f32 v[172:173], v[176:177], v[172:173]
	v_rcp_f32_e32 v176, v1
	v_and_b32_e32 v1, 0xffff0000, v174
	v_mul_f32_e32 v1, 0xbfb8aa3b, v1
	v_exp_f32_e32 v1, v1
	v_pk_mul_f32 v[114:115], v[114:115], v[172:173]
	v_exp_f32_e32 v172, v3
	v_and_b32_e32 v3, 0xffff0000, v178
	v_add_f32_e32 v1, 1.0, v1
	v_rcp_f32_e32 v177, v1
	v_lshlrev_b32_e32 v1, 16, v175
	v_mul_f32_e32 v1, 0xbfb8aa3b, v1
	v_exp_f32_e32 v1, v1
	v_mul_f32_e32 v3, 0xbfb8aa3b, v3
	v_exp_f32_e32 v173, v3
	v_lshlrev_b32_e32 v3, 16, v179
	v_add_f32_e32 v1, 1.0, v1
	v_rcp_f32_e32 v178, v1
	v_and_b32_e32 v1, 0xffff0000, v175
	v_mul_f32_e32 v1, 0xbfb8aa3b, v1
	v_exp_f32_e32 v1, v1
	v_mul_f32_e32 v3, 0xbfb8aa3b, v3
	v_exp_f32_e32 v174, v3
	v_and_b32_e32 v3, 0xffff0000, v179
	v_mul_f32_e32 v3, 0xbfb8aa3b, v3
	v_add_f32_e32 v1, 1.0, v1
	v_exp_f32_e32 v175, v3
	v_rcp_f32_e32 v179, v1
	v_lshlrev_b32_e32 v1, 16, v164
	v_mul_f32_e32 v1, 0xbfb8aa3b, v1
	v_exp_f32_e32 v1, v1
	v_pk_add_f32 v[174:175], v[174:175], 1.0 op_sel_hi:[1,0]
	v_pk_add_f32 v[172:173], v[172:173], 1.0 op_sel_hi:[1,0]
	v_pk_mul_f32 v[174:175], v[218:219], v[174:175] op_sel_hi:[0,1]
	v_pk_mul_f32 v[174:175], v[178:179], v[174:175]
	v_add_f32_e32 v1, 1.0, v1
	v_pk_mul_f32 v[110:111], v[110:111], v[174:175]
	v_rcp_f32_e32 v174, v1
	v_and_b32_e32 v1, 0xffff0000, v164
	v_mul_f32_e32 v1, 0xbfb8aa3b, v1
	v_exp_f32_e32 v1, v1
	v_pk_mul_f32 v[172:173], v[218:219], v[172:173] op_sel_hi:[0,1]
	v_lshlrev_b32_e32 v3, 16, v168
	v_pk_mul_f32 v[172:173], v[176:177], v[172:173]
	v_add_f32_e32 v1, 1.0, v1
	v_rcp_f32_e32 v175, v1
	v_lshlrev_b32_e32 v1, 16, v165
	v_mul_f32_e32 v1, 0xbfb8aa3b, v1
	v_exp_f32_e32 v1, v1
	v_mul_f32_e32 v3, 0xbfb8aa3b, v3
	v_pk_mul_f32 v[108:109], v[108:109], v[172:173]
	v_exp_f32_e32 v172, v3
	v_add_f32_e32 v1, 1.0, v1
	v_and_b32_e32 v3, 0xffff0000, v168
	v_rcp_f32_e32 v168, v1
	v_and_b32_e32 v1, 0xffff0000, v165
	v_mul_f32_e32 v1, 0xbfb8aa3b, v1
	v_exp_f32_e32 v1, v1
	v_mul_f32_e32 v3, 0xbfb8aa3b, v3
	v_exp_f32_e32 v173, v3
	v_lshlrev_b32_e32 v3, 16, v169
	v_mul_f32_e32 v3, 0xbfb8aa3b, v3
	v_exp_f32_e32 v164, v3
	v_and_b32_e32 v3, 0xffff0000, v169
	v_add_f32_e32 v1, 1.0, v1
	v_mul_f32_e32 v3, 0xbfb8aa3b, v3
	v_rcp_f32_e32 v169, v1
	v_lshlrev_b32_e32 v1, 16, v166
	v_exp_f32_e32 v165, v3
	v_mul_f32_e32 v1, 0xbfb8aa3b, v1
	v_exp_f32_e32 v1, v1
	v_lshlrev_b32_e32 v3, 16, v170
	v_pk_add_f32 v[164:165], v[164:165], 1.0 op_sel_hi:[1,0]
	v_mul_f32_e32 v3, 0xbfb8aa3b, v3
	v_pk_mul_f32 v[164:165], v[218:219], v[164:165] op_sel_hi:[0,1]
	v_add_f32_e32 v1, 1.0, v1
	v_pk_mul_f32 v[164:165], v[168:169], v[164:165]
	v_rcp_f32_e32 v168, v1
	v_and_b32_e32 v1, 0xffff0000, v166
	v_mul_f32_e32 v1, 0xbfb8aa3b, v1
	v_exp_f32_e32 v1, v1
	v_pk_mul_f32 v[106:107], v[106:107], v[164:165]
	v_exp_f32_e32 v164, v3
	v_and_b32_e32 v3, 0xffff0000, v170
	v_add_f32_e32 v1, 1.0, v1
	v_rcp_f32_e32 v169, v1
; DI float lo16(unsigned u) { return __uint_as_float(u << 16); }
; DI float hi16(unsigned u) { return __uint_as_float(u & 0xffff0000u); }
;     DI void mid(f32x4 (&acc)[2][2][4][2], const Unit& u, int wr, int wc, int fr, int fq) const {
;     ...
;             for (int m = 0; m < 4; ++m) { const int row = row0 + ai * HALF + m * 16; const bf16_t* rowp = P + (size_t)row * LDP + col0; rs[m] = rstd[row];
; #pragma unroll
;                 for (int bj = 0; bj < 2; ++bj) { gs[m][bj] = *(const u32x4*)(rowp + bj * HALF + C_GLS); gn[m][bj] = *(const u32x4*)(rowp + bj * HALF + C_GLN); } }
; #pragma unroll
;             for (int m = 0; m < 4; ++m)
; #pragma unroll
;                 for (int bj = 0; bj < 2; ++bj) {
;                     const unsigned gsw[4] = {gs[m][bj].x, gs[m][bj].y, gs[m][bj].z, gs[m][bj].w}, gnw[4] = {gn[m][bj].x, gn[m][bj].y, gn[m][bj].z, gn[m][bj].w};
; #pragma unroll
;                     for (int j = 0; j < 4; ++j) {
;                         const float r0 = rs[m] * (1.f + __expf(-lo16(gnw[j]))) * __builtin_amdgcn_rcpf(1.f + __expf(-lo16(gsw[j])));
;                         const float r1 = rs[m] * (1.f + __expf(-hi16(gnw[j]))) * __builtin_amdgcn_rcpf(1.f + __expf(-hi16(gsw[j])));
;                         acc[ai][bj][m][j >> 1][(j & 1) * 2] *= r0; acc[ai][bj][m][j >> 1][(j & 1) * 2 + 1] *= r1; } }
	v_lshlrev_b32_e32 v1, 16, v167
	v_mul_f32_e32 v1, 0xbfb8aa3b, v1
	v_exp_f32_e32 v1, v1
	v_mul_f32_e32 v3, 0xbfb8aa3b, v3
	v_exp_f32_e32 v165, v3
	v_lshlrev_b32_e32 v3, 16, v171
	v_add_f32_e32 v1, 1.0, v1
	v_rcp_f32_e32 v170, v1
	v_and_b32_e32 v1, 0xffff0000, v167
	v_mul_f32_e32 v1, 0xbfb8aa3b, v1
	v_exp_f32_e32 v1, v1
	v_mul_f32_e32 v3, 0xbfb8aa3b, v3
	v_exp_f32_e32 v166, v3
	v_and_b32_e32 v3, 0xffff0000, v171
	v_mul_f32_e32 v3, 0xbfb8aa3b, v3
	v_add_f32_e32 v1, 1.0, v1
	v_exp_f32_e32 v167, v3
	v_rcp_f32_e32 v171, v1
	v_lshlrev_b32_e32 v1, 16, v156
	v_mul_f32_e32 v1, 0xbfb8aa3b, v1
	v_exp_f32_e32 v1, v1
	v_pk_add_f32 v[166:167], v[166:167], 1.0 op_sel_hi:[1,0]
	v_pk_add_f32 v[164:165], v[164:165], 1.0 op_sel_hi:[1,0]
	v_pk_mul_f32 v[166:167], v[218:219], v[166:167] op_sel_hi:[0,1]
	v_pk_mul_f32 v[166:167], v[170:171], v[166:167]
	v_add_f32_e32 v1, 1.0, v1
	v_pk_mul_f32 v[102:103], v[102:103], v[166:167]
	v_rcp_f32_e32 v166, v1
	v_and_b32_e32 v1, 0xffff0000, v156
	v_mul_f32_e32 v1, 0xbfb8aa3b, v1
	v_exp_f32_e32 v1, v1
	v_pk_mul_f32 v[164:165], v[218:219], v[164:165] op_sel_hi:[0,1]
	v_lshlrev_b32_e32 v3, 16, v160
	v_pk_mul_f32 v[164:165], v[168:169], v[164:165]
	v_add_f32_e32 v1, 1.0, v1
	v_rcp_f32_e32 v167, v1
	v_lshlrev_b32_e32 v1, 16, v157
	v_mul_f32_e32 v1, 0xbfb8aa3b, v1
	v_exp_f32_e32 v1, v1
	v_mul_f32_e32 v3, 0xbfb8aa3b, v3
	v_pk_mul_f32 v[100:101], v[100:101], v[164:165]
	v_exp_f32_e32 v164, v3
	v_add_f32_e32 v1, 1.0, v1
	v_and_b32_e32 v3, 0xffff0000, v160
	v_rcp_f32_e32 v160, v1
	v_and_b32_e32 v1, 0xffff0000, v157
	v_mul_f32_e32 v1, 0xbfb8aa3b, v1
	v_exp_f32_e32 v1, v1
	v_mul_f32_e32 v3, 0xbfb8aa3b, v3
	v_exp_f32_e32 v165, v3
	v_lshlrev_b32_e32 v3, 16, v161
	v_mul_f32_e32 v3, 0xbfb8aa3b, v3
	v_exp_f32_e32 v156, v3
	v_and_b32_e32 v3, 0xffff0000, v161
	v_add_f32_e32 v1, 1.0, v1
	v_mul_f32_e32 v3, 0xbfb8aa3b, v3
	v_rcp_f32_e32 v161, v1
	v_lshlrev_b32_e32 v1, 16, v158
	v_exp_f32_e32 v157, v3
	v_mul_f32_e32 v1, 0xbfb8aa3b, v1
	v_exp_f32_e32 v1, v1
	v_addc_co_u32_e32 v135, vcc, 0, v141, vcc
	v_add_co_u32_e32 v132, vcc, s49, v140
	v_pk_add_f32 v[156:157], v[156:157], 1.0 op_sel_hi:[1,0]
	s_nop 0
	v_addc_co_u32_e32 v133, vcc, 0, v141, vcc
	v_pk_mul_f32 v[156:157], v[216:217], v[156:157] op_sel_hi:[0,1]
	v_add_f32_e32 v1, 1.0, v1
	global_load_dwordx4 v[140:143], v[134:135], off offset:1024
	global_load_dwordx4 v[136:139], v[134:135], off offset:1280
	global_load_dwordx4 v[144:147], v[132:133], off offset:1024
	s_nop 0
	global_load_dwordx4 v[132:135], v[132:133], off offset:1280
	v_pk_mul_f32 v[156:157], v[160:161], v[156:157]
	v_rcp_f32_e32 v160, v1
	v_and_b32_e32 v1, 0xffff0000, v158
	v_mul_f32_e32 v1, 0xbfb8aa3b, v1
	v_exp_f32_e32 v1, v1
	v_lshlrev_b32_e32 v3, 16, v162
	v_mul_f32_e32 v3, 0xbfb8aa3b, v3
	v_pk_mul_f32 v[98:99], v[98:99], v[156:157]
	v_add_f32_e32 v1, 1.0, v1
	v_rcp_f32_e32 v161, v1
	v_lshlrev_b32_e32 v1, 16, v159
	v_mul_f32_e32 v1, 0xbfb8aa3b, v1
	v_exp_f32_e32 v1, v1
	v_exp_f32_e32 v156, v3
	v_and_b32_e32 v3, 0xffff0000, v162
	v_mul_f32_e32 v3, 0xbfb8aa3b, v3
	v_add_f32_e32 v1, 1.0, v1
	v_rcp_f32_e32 v162, v1
	v_and_b32_e32 v1, 0xffff0000, v159
	v_mul_f32_e32 v1, 0xbfb8aa3b, v1
	v_exp_f32_e32 v1, v1
	v_exp_f32_e32 v157, v3
	v_lshlrev_b32_e32 v3, 16, v163
	v_mul_f32_e32 v3, 0xbfb8aa3b, v3
	v_exp_f32_e32 v158, v3
	v_and_b32_e32 v3, 0xffff0000, v163
	v_mul_f32_e32 v3, 0xbfb8aa3b, v3
	v_add_f32_e32 v1, 1.0, v1
	v_exp_f32_e32 v159, v3
	v_rcp_f32_e32 v163, v1
	v_lshlrev_b32_e32 v1, 16, v148
	v_mul_f32_e32 v1, 0xbfb8aa3b, v1
	v_exp_f32_e32 v1, v1
	v_pk_add_f32 v[158:159], v[158:159], 1.0 op_sel_hi:[1,0]
	v_pk_add_f32 v[156:157], v[156:157], 1.0 op_sel_hi:[1,0]
	v_pk_mul_f32 v[158:159], v[216:217], v[158:159] op_sel_hi:[0,1]
	v_pk_mul_f32 v[158:159], v[162:163], v[158:159]
	v_add_f32_e32 v1, 1.0, v1
	v_pk_mul_f32 v[94:95], v[94:95], v[158:159]
	v_rcp_f32_e32 v158, v1
	v_and_b32_e32 v1, 0xffff0000, v148
	v_mul_f32_e32 v1, 0xbfb8aa3b, v1
	v_exp_f32_e32 v1, v1
	v_pk_mul_f32 v[156:157], v[216:217], v[156:157] op_sel_hi:[0,1]
	v_lshlrev_b32_e32 v3, 16, v152
	v_pk_mul_f32 v[156:157], v[160:161], v[156:157]
	v_add_f32_e32 v1, 1.0, v1
	v_rcp_f32_e32 v159, v1
	v_lshlrev_b32_e32 v1, 16, v149
	v_mul_f32_e32 v1, 0xbfb8aa3b, v1
	v_exp_f32_e32 v1, v1
	v_mul_f32_e32 v3, 0xbfb8aa3b, v3
	v_pk_mul_f32 v[92:93], v[92:93], v[156:157]
	v_exp_f32_e32 v156, v3
	v_add_f32_e32 v1, 1.0, v1
	v_and_b32_e32 v3, 0xffff0000, v152
	v_rcp_f32_e32 v152, v1
	v_and_b32_e32 v1, 0xffff0000, v149
	v_mul_f32_e32 v1, 0xbfb8aa3b, v1
	v_exp_f32_e32 v1, v1
	v_mul_f32_e32 v3, 0xbfb8aa3b, v3
	v_exp_f32_e32 v157, v3
	v_lshlrev_b32_e32 v3, 16, v153
	v_mul_f32_e32 v3, 0xbfb8aa3b, v3
	v_exp_f32_e32 v148, v3
	v_and_b32_e32 v3, 0xffff0000, v153
	v_add_f32_e32 v1, 1.0, v1
	v_mul_f32_e32 v3, 0xbfb8aa3b, v3
	v_rcp_f32_e32 v153, v1
	v_lshlrev_b32_e32 v1, 16, v150
	v_exp_f32_e32 v149, v3
	v_mul_f32_e32 v1, 0xbfb8aa3b, v1
	v_exp_f32_e32 v1, v1
	v_lshlrev_b32_e32 v3, 16, v154
	v_pk_add_f32 v[148:149], v[148:149], 1.0 op_sel_hi:[1,0]
	v_mul_f32_e32 v3, 0xbfb8aa3b, v3
	v_pk_mul_f32 v[148:149], v[216:217], v[148:149] op_sel_hi:[0,1]
	v_add_f32_e32 v1, 1.0, v1
	v_pk_mul_f32 v[148:149], v[152:153], v[148:149]
	v_rcp_f32_e32 v152, v1
	v_and_b32_e32 v1, 0xffff0000, v150
	v_mul_f32_e32 v1, 0xbfb8aa3b, v1
	v_exp_f32_e32 v1, v1
	v_pk_mul_f32 v[90:91], v[90:91], v[148:149]
	v_exp_f32_e32 v148, v3
	v_and_b32_e32 v3, 0xffff0000, v154
	v_add_f32_e32 v1, 1.0, v1
	v_rcp_f32_e32 v153, v1
	v_lshlrev_b32_e32 v1, 16, v151
	v_mul_f32_e32 v1, 0xbfb8aa3b, v1
	v_exp_f32_e32 v1, v1
	v_mul_f32_e32 v3, 0xbfb8aa3b, v3
	v_exp_f32_e32 v149, v3
	v_lshlrev_b32_e32 v3, 16, v155
	v_add_f32_e32 v1, 1.0, v1
	v_rcp_f32_e32 v154, v1
	v_and_b32_e32 v1, 0xffff0000, v151
	v_mul_f32_e32 v1, 0xbfb8aa3b, v1
	v_exp_f32_e32 v1, v1
	v_mul_f32_e32 v3, 0xbfb8aa3b, v3
	v_exp_f32_e32 v150, v3
	v_and_b32_e32 v3, 0xffff0000, v155
	v_mul_f32_e32 v3, 0xbfb8aa3b, v3
	v_add_f32_e32 v1, 1.0, v1
	v_exp_f32_e32 v151, v3
	v_rcp_f32_e32 v155, v1
	s_waitcnt vmcnt(0)
; DI float lo16(unsigned u) { return __uint_as_float(u << 16); }
; DI float hi16(unsigned u) { return __uint_as_float(u & 0xffff0000u); }
;     DI void mid(f32x4 (&acc)[2][2][4][2], const Unit& u, int wr, int wc, int fr, int fq) const {
;     ...
;             for (int m = 0; m < 4; ++m) { const int row = row0 + ai * HALF + m * 16; const bf16_t* rowp = P + (size_t)row * LDP + col0; rs[m] = rstd[row];
; #pragma unroll
;                 for (int bj = 0; bj < 2; ++bj) { gs[m][bj] = *(const u32x4*)(rowp + bj * HALF + C_GLS); gn[m][bj] = *(const u32x4*)(rowp + bj * HALF + C_GLN); } }
; #pragma unroll
;             for (int m = 0; m < 4; ++m)
; #pragma unroll
;                 for (int bj = 0; bj < 2; ++bj) {
;                     const unsigned gsw[4] = {gs[m][bj].x, gs[m][bj].y, gs[m][bj].z, gs[m][bj].w}, gnw[4] = {gn[m][bj].x, gn[m][bj].y, gn[m][bj].z, gn[m][bj].w};
; #pragma unroll
;                     for (int j = 0; j < 4; ++j) {
;                         const float r0 = rs[m] * (1.f + __expf(-lo16(gnw[j]))) * __builtin_amdgcn_rcpf(1.f + __expf(-lo16(gsw[j])));
;                         const float r1 = rs[m] * (1.f + __expf(-hi16(gnw[j]))) * __builtin_amdgcn_rcpf(1.f + __expf(-hi16(gsw[j])));
;                         acc[ai][bj][m][j >> 1][(j & 1) * 2] *= r0; acc[ai][bj][m][j >> 1][(j & 1) * 2 + 1] *= r1; } }
	v_lshlrev_b32_e32 v1, 16, v140
	v_mul_f32_e32 v1, 0xbfb8aa3b, v1
	v_exp_f32_e32 v1, v1
	v_pk_add_f32 v[150:151], v[150:151], 1.0 op_sel_hi:[1,0]
	v_pk_add_f32 v[148:149], v[148:149], 1.0 op_sel_hi:[1,0]
	v_pk_mul_f32 v[150:151], v[216:217], v[150:151] op_sel_hi:[0,1]
	v_pk_mul_f32 v[150:151], v[154:155], v[150:151]
	v_add_f32_e32 v1, 1.0, v1
	v_pk_mul_f32 v[86:87], v[86:87], v[150:151]
	v_rcp_f32_e32 v150, v1
	v_and_b32_e32 v1, 0xffff0000, v140
	v_mul_f32_e32 v1, 0xbfb8aa3b, v1
	v_exp_f32_e32 v1, v1
	v_pk_mul_f32 v[148:149], v[216:217], v[148:149] op_sel_hi:[0,1]
	v_lshlrev_b32_e32 v3, 16, v144
	v_pk_mul_f32 v[148:149], v[152:153], v[148:149]
	v_add_f32_e32 v1, 1.0, v1
	v_rcp_f32_e32 v151, v1
	v_lshlrev_b32_e32 v1, 16, v141
	v_mul_f32_e32 v1, 0xbfb8aa3b, v1
	v_exp_f32_e32 v1, v1
	v_mul_f32_e32 v3, 0xbfb8aa3b, v3
	v_pk_mul_f32 v[84:85], v[84:85], v[148:149]
	v_exp_f32_e32 v148, v3
	v_add_f32_e32 v1, 1.0, v1
	v_and_b32_e32 v3, 0xffff0000, v144
	v_rcp_f32_e32 v144, v1
	v_and_b32_e32 v1, 0xffff0000, v141
	v_mul_f32_e32 v1, 0xbfb8aa3b, v1
	v_exp_f32_e32 v1, v1
	v_mul_f32_e32 v3, 0xbfb8aa3b, v3
	v_exp_f32_e32 v149, v3
	v_lshlrev_b32_e32 v3, 16, v145
	v_mul_f32_e32 v3, 0xbfb8aa3b, v3
	v_exp_f32_e32 v140, v3
	v_and_b32_e32 v3, 0xffff0000, v145
	v_add_f32_e32 v1, 1.0, v1
	v_mul_f32_e32 v3, 0xbfb8aa3b, v3
	v_rcp_f32_e32 v145, v1
	v_lshlrev_b32_e32 v1, 16, v142
	v_exp_f32_e32 v141, v3
	v_mul_f32_e32 v1, 0xbfb8aa3b, v1
	v_exp_f32_e32 v1, v1
	v_lshlrev_b32_e32 v3, 16, v146
	v_pk_add_f32 v[140:141], v[140:141], 1.0 op_sel_hi:[1,0]
	v_mul_f32_e32 v3, 0xbfb8aa3b, v3
	v_pk_mul_f32 v[140:141], v[214:215], v[140:141] op_sel_hi:[0,1]
	v_add_f32_e32 v1, 1.0, v1
	v_pk_mul_f32 v[140:141], v[144:145], v[140:141]
	v_rcp_f32_e32 v144, v1
	v_and_b32_e32 v1, 0xffff0000, v142
	v_mul_f32_e32 v1, 0xbfb8aa3b, v1
	v_exp_f32_e32 v1, v1
	v_pk_mul_f32 v[82:83], v[82:83], v[140:141]
	v_exp_f32_e32 v140, v3
	v_and_b32_e32 v3, 0xffff0000, v146
	v_add_f32_e32 v1, 1.0, v1
	v_rcp_f32_e32 v145, v1
	v_lshlrev_b32_e32 v1, 16, v143
	v_mul_f32_e32 v1, 0xbfb8aa3b, v1
	v_exp_f32_e32 v1, v1
	v_mul_f32_e32 v3, 0xbfb8aa3b, v3
	v_exp_f32_e32 v141, v3
	v_lshlrev_b32_e32 v3, 16, v147
	v_add_f32_e32 v1, 1.0, v1
	v_rcp_f32_e32 v146, v1
	v_and_b32_e32 v1, 0xffff0000, v143
	v_mul_f32_e32 v1, 0xbfb8aa3b, v1
	v_exp_f32_e32 v1, v1
	v_mul_f32_e32 v3, 0xbfb8aa3b, v3
	v_exp_f32_e32 v142, v3
	v_and_b32_e32 v3, 0xffff0000, v147
	v_mul_f32_e32 v3, 0xbfb8aa3b, v3
	v_add_f32_e32 v1, 1.0, v1
	v_exp_f32_e32 v143, v3
	v_rcp_f32_e32 v147, v1
	v_lshlrev_b32_e32 v1, 16, v136
	v_mul_f32_e32 v1, 0xbfb8aa3b, v1
	v_exp_f32_e32 v1, v1
	v_pk_add_f32 v[142:143], v[142:143], 1.0 op_sel_hi:[1,0]
	v_pk_add_f32 v[140:141], v[140:141], 1.0 op_sel_hi:[1,0]
	v_pk_mul_f32 v[142:143], v[214:215], v[142:143] op_sel_hi:[0,1]
	v_pk_mul_f32 v[142:143], v[146:147], v[142:143]
	v_add_f32_e32 v1, 1.0, v1
	v_pk_mul_f32 v[78:79], v[78:79], v[142:143]
	v_rcp_f32_e32 v142, v1
	v_and_b32_e32 v1, 0xffff0000, v136
	v_mul_f32_e32 v1, 0xbfb8aa3b, v1
	v_exp_f32_e32 v1, v1
	v_pk_mul_f32 v[140:141], v[214:215], v[140:141] op_sel_hi:[0,1]
	v_lshlrev_b32_e32 v3, 16, v132
	v_pk_mul_f32 v[140:141], v[144:145], v[140:141]
	v_add_f32_e32 v1, 1.0, v1
	v_rcp_f32_e32 v143, v1
	v_lshlrev_b32_e32 v1, 16, v137
	v_mul_f32_e32 v1, 0xbfb8aa3b, v1
	v_exp_f32_e32 v1, v1
	v_mul_f32_e32 v3, 0xbfb8aa3b, v3
	v_pk_mul_f32 v[76:77], v[76:77], v[140:141]
	v_exp_f32_e32 v140, v3
	v_and_b32_e32 v3, 0xffff0000, v132
	v_add_f32_e32 v1, 1.0, v1
	v_mul_f32_e32 v3, 0xbfb8aa3b, v3
	v_rcp_f32_e32 v136, v1
	v_and_b32_e32 v1, 0xffff0000, v137
	v_exp_f32_e32 v141, v3
	v_lshlrev_b32_e32 v3, 16, v133
	v_mul_f32_e32 v1, 0xbfb8aa3b, v1
	v_mul_f32_e32 v3, 0xbfb8aa3b, v3
	v_exp_f32_e32 v1, v1
	v_exp_f32_e32 v132, v3
	v_and_b32_e32 v3, 0xffff0000, v133
	v_mul_f32_e32 v3, 0xbfb8aa3b, v3
	v_exp_f32_e32 v133, v3
	v_add_f32_e32 v1, 1.0, v1
	v_rcp_f32_e32 v137, v1
	v_lshlrev_b32_e32 v3, 16, v134
	v_pk_add_f32 v[132:133], v[132:133], 1.0 op_sel_hi:[1,0]
	v_mul_f32_e32 v3, 0xbfb8aa3b, v3
	v_pk_mul_f32 v[132:133], v[214:215], v[132:133] op_sel_hi:[0,1]
	v_pk_mul_f32 v[132:133], v[136:137], v[132:133]
	v_pk_add_f32 v[140:141], v[140:141], 1.0 op_sel_hi:[1,0]
	v_pk_mul_f32 v[74:75], v[74:75], v[132:133]
	v_exp_f32_e32 v132, v3
	v_and_b32_e32 v3, 0xffff0000, v134
	v_pk_mul_f32 v[140:141], v[214:215], v[140:141] op_sel_hi:[0,1]
	v_mul_f32_e32 v3, 0xbfb8aa3b, v3
	v_pk_mul_f32 v[140:141], v[142:143], v[140:141]
	v_exp_f32_e32 v133, v3
	v_add_u32_e32 v3, 0x80, v2
	v_pk_add_f32 v[224:225], v[224:225], 1.0 op_sel_hi:[1,0]
	v_pk_mul_f32 v[72:73], v[72:73], v[140:141]
	v_mad_i64_i32 v[140:141], s[0:1], v3, s54, v[210:211]
	v_pk_mul_f32 v[224:225], v[220:221], v[224:225] op_sel_hi:[0,1]
	v_add_co_u32_e32 v142, vcc, s55, v140
	v_pk_mul_f32 v[224:225], v[226:227], v[224:225]
	s_nop 0
	v_addc_co_u32_e32 v143, vcc, 0, v141, vcc
	v_pk_mul_f32 v[120:121], v[120:121], v[224:225]
	global_load_dwordx4 v[224:227], v[142:143], off offset:1024
	v_add_co_u32_e32 v140, vcc, s49, v140
	v_pk_add_f32 v[180:181], v[180:181], 1.0 op_sel_hi:[1,0]
	s_nop 0
	v_addc_co_u32_e32 v141, vcc, 0, v141, vcc
	global_load_dwordx4 v[228:231], v[140:141], off offset:1024
	v_pk_mul_f32 v[180:181], v[218:219], v[180:181] op_sel_hi:[0,1]
	v_pk_mul_f32 v[180:181], v[182:183], v[180:181]
	v_pk_add_f32 v[164:165], v[164:165], 1.0 op_sel_hi:[1,0]
	v_pk_add_f32 v[156:157], v[156:157], 1.0 op_sel_hi:[1,0]
	v_pk_mul_f32 v[112:113], v[112:113], v[180:181]
	v_pk_mul_f32 v[164:165], v[216:217], v[164:165] op_sel_hi:[0,1]
	v_pk_mul_f32 v[156:157], v[216:217], v[156:157] op_sel_hi:[0,1]
	global_load_dword v216, v[212:213], off offset:512
; DI float lo16(unsigned u) { return __uint_as_float(u << 16); }
; DI float hi16(unsigned u) { return __uint_as_float(u & 0xffff0000u); }
;     DI void mid(f32x4 (&acc)[2][2][4][2], const Unit& u, int wr, int wc, int fr, int fq) const {
;     ...
;             for (int m = 0; m < 4; ++m) { const int row = row0 + ai * HALF + m * 16; const bf16_t* rowp = P + (size_t)row * LDP + col0; rs[m] = rstd[row];
; #pragma unroll
;                 for (int bj = 0; bj < 2; ++bj) { gs[m][bj] = *(const u32x4*)(rowp + bj * HALF + C_GLS); gn[m][bj] = *(const u32x4*)(rowp + bj * HALF + C_GLN); } }
; #pragma unroll
;             for (int m = 0; m < 4; ++m)
; #pragma unroll
;                 for (int bj = 0; bj < 2; ++bj) {
;                     const unsigned gsw[4] = {gs[m][bj].x, gs[m][bj].y, gs[m][bj].z, gs[m][bj].w}, gnw[4] = {gn[m][bj].x, gn[m][bj].y, gn[m][bj].z, gn[m][bj].w};
; #pragma unroll
;                     for (int j = 0; j < 4; ++j) {
;                         const float r0 = rs[m] * (1.f + __expf(-lo16(gnw[j]))) * __builtin_amdgcn_rcpf(1.f + __expf(-lo16(gsw[j])));
;                         const float r1 = rs[m] * (1.f + __expf(-hi16(gnw[j]))) * __builtin_amdgcn_rcpf(1.f + __expf(-hi16(gsw[j])));
;                         acc[ai][bj][m][j >> 1][(j & 1) * 2] *= r0; acc[ai][bj][m][j >> 1][(j & 1) * 2 + 1] *= r1; } }
	global_load_dwordx4 v[184:187], v[142:143], off offset:1280
	global_load_dwordx4 v[180:183], v[140:141], off offset:1280
	v_lshlrev_b32_e32 v1, 16, v138
	v_mul_f32_e32 v1, 0xbfb8aa3b, v1
	v_exp_f32_e32 v1, v1
	v_lshlrev_b32_e32 v3, 16, v135
	v_mul_f32_e32 v3, 0xbfb8aa3b, v3
	v_exp_f32_e32 v134, v3
	v_add_f32_e32 v1, 1.0, v1
	v_rcp_f32_e32 v136, v1
	v_and_b32_e32 v1, 0xffff0000, v138
	v_mul_f32_e32 v1, 0xbfb8aa3b, v1
	v_exp_f32_e32 v1, v1
	v_and_b32_e32 v3, 0xffff0000, v135
	v_mul_f32_e32 v3, 0xbfb8aa3b, v3
	v_exp_f32_e32 v135, v3
	v_add_f32_e32 v1, 1.0, v1
	v_rcp_f32_e32 v137, v1
	v_lshlrev_b32_e32 v1, 16, v139
	v_mul_f32_e32 v1, 0xbfb8aa3b, v1
	v_exp_f32_e32 v1, v1
	v_pk_add_f32 v[132:133], v[132:133], 1.0 op_sel_hi:[1,0]
	v_pk_add_f32 v[134:135], v[134:135], 1.0 op_sel_hi:[1,0]
	v_pk_mul_f32 v[132:133], v[214:215], v[132:133] op_sel_hi:[0,1]
	v_add_f32_e32 v1, 1.0, v1
	v_rcp_f32_e32 v138, v1
	v_and_b32_e32 v1, 0xffff0000, v139
	v_mul_f32_e32 v1, 0xbfb8aa3b, v1
	v_exp_f32_e32 v1, v1
	v_pk_mul_f32 v[134:135], v[214:215], v[134:135] op_sel_hi:[0,1]
	v_pk_mul_f32 v[132:133], v[136:137], v[132:133]
	v_pk_add_f32 v[172:173], v[172:173], 1.0 op_sel_hi:[1,0]
	v_add_f32_e32 v1, 1.0, v1
	v_rcp_f32_e32 v139, v1
	v_add_u32_e32 v1, 0x90, v2
	v_pk_mul_f32 v[68:69], v[68:69], v[132:133]
	v_mad_i64_i32 v[132:133], s[0:1], v1, s54, v[210:211]
	v_pk_mul_f32 v[134:135], v[138:139], v[134:135]
	v_pk_mul_f32 v[172:173], v[218:219], v[172:173] op_sel_hi:[0,1]
	v_pk_mul_f32 v[70:71], v[70:71], v[134:135]
	v_add_co_u32_e32 v134, vcc, s55, v132
	v_pk_mul_f32 v[172:173], v[174:175], v[172:173]
	s_nop 0
	v_addc_co_u32_e32 v135, vcc, 0, v133, vcc
	v_add_co_u32_e32 v132, vcc, s49, v132
	v_pk_mul_f32 v[164:165], v[166:167], v[164:165]
	s_nop 0
	v_addc_co_u32_e32 v133, vcc, 0, v133, vcc
	v_add_u32_e32 v1, 0xa0, v2
	v_pk_mul_f32 v[104:105], v[104:105], v[172:173]
	v_pk_mul_f32 v[96:97], v[96:97], v[164:165]
	global_load_dwordx4 v[172:175], v[134:135], off offset:1024
	global_load_dwordx4 v[168:171], v[134:135], off offset:1280
	global_load_dwordx4 v[176:179], v[132:133], off offset:1024
	global_load_dwordx4 v[164:167], v[132:133], off offset:1280
	v_mad_i64_i32 v[132:133], s[0:1], v1, s54, v[210:211]
	v_add_co_u32_e32 v134, vcc, s55, v132
	v_pk_add_f32 v[148:149], v[148:149], 1.0 op_sel_hi:[1,0]
	s_nop 0
	v_addc_co_u32_e32 v135, vcc, 0, v133, vcc
	v_pk_mul_f32 v[148:149], v[214:215], v[148:149] op_sel_hi:[0,1]
	v_add_co_u32_e32 v132, vcc, s49, v132
	v_mul_f32_e32 v205, 0xbfb8aa3b, v205
	v_pk_mul_f32 v[156:157], v[158:159], v[156:157]
	v_pk_mul_f32 v[148:149], v[150:151], v[148:149]
	v_addc_co_u32_e32 v133, vcc, 0, v133, vcc
	v_add_u32_e32 v1, 0xb0, v2
	v_exp_f32_e32 v232, v205
	v_pk_mul_f32 v[88:89], v[88:89], v[156:157]
	v_pk_mul_f32 v[80:81], v[80:81], v[148:149]
	global_load_dwordx4 v[156:159], v[134:135], off offset:1024
	global_load_dwordx4 v[152:155], v[134:135], off offset:1280
	global_load_dwordx4 v[160:163], v[132:133], off offset:1024
	global_load_dwordx4 v[148:151], v[132:133], off offset:1280
	v_mad_i64_i32 v[132:133], s[0:1], v1, s54, v[210:211]
	s_waitcnt vmcnt(0)
	v_lshlrev_b32_e32 v1, 16, v224
	v_mul_f32_e32 v1, 0xbfb8aa3b, v1
	v_exp_f32_e32 v1, v1
	v_pk_add_f32 v[232:233], v[232:233], 1.0 op_sel_hi:[1,0]
	v_lshlrev_b32_e32 v3, 16, v228
	v_pk_mul_f32 v[232:233], v[220:221], v[232:233] op_sel_hi:[0,1]
	v_pk_mul_f32 v[232:233], v[234:235], v[232:233]
	v_add_f32_e32 v1, 1.0, v1
	v_pk_mul_f32 v[128:129], v[128:129], v[232:233]
	v_rcp_f32_e32 v232, v1
	v_and_b32_e32 v1, 0xffff0000, v224
	v_mul_f32_e32 v1, 0xbfb8aa3b, v1
	v_exp_f32_e32 v1, v1
	v_mul_f32_e32 v3, 0xbfb8aa3b, v3
	global_load_dword v214, v[212:213], off offset:576
	global_load_dword v210, v[212:213], off offset:640
	global_load_dword v2, v[212:213], off offset:704
	v_exp_f32_e32 v212, v3
	v_add_f32_e32 v1, 1.0, v1
	v_rcp_f32_e32 v233, v1
	v_lshlrev_b32_e32 v1, 16, v225
	v_mul_f32_e32 v1, 0xbfb8aa3b, v1
	v_exp_f32_e32 v1, v1
	v_and_b32_e32 v3, 0xffff0000, v228
	v_mul_f32_e32 v3, 0xbfb8aa3b, v3
	v_exp_f32_e32 v213, v3
	v_add_f32_e32 v1, 1.0, v1
	v_rcp_f32_e32 v228, v1
	v_and_b32_e32 v1, 0xffff0000, v225
	v_mul_f32_e32 v1, 0xbfb8aa3b, v1
	v_exp_f32_e32 v1, v1
	v_lshlrev_b32_e32 v3, 16, v229
	v_mul_f32_e32 v3, 0xbfb8aa3b, v3
	v_exp_f32_e32 v224, v3
	v_and_b32_e32 v3, 0xffff0000, v229
	v_mul_f32_e32 v3, 0xbfb8aa3b, v3
	v_add_f32_e32 v1, 1.0, v1
	v_exp_f32_e32 v225, v3
	v_rcp_f32_e32 v229, v1
	v_lshlrev_b32_e32 v1, 16, v226
	v_mul_f32_e32 v1, 0xbfb8aa3b, v1
	v_exp_f32_e32 v1, v1
	v_pk_add_f32 v[224:225], v[224:225], 1.0 op_sel_hi:[1,0]
	v_pk_add_f32 v[212:213], v[212:213], 1.0 op_sel_hi:[1,0]
	v_pk_mul_f32 v[224:225], v[216:217], v[224:225] op_sel_hi:[0,1]
	v_pk_mul_f32 v[224:225], v[228:229], v[224:225]
	v_add_f32_e32 v1, 1.0, v1
	v_pk_mul_f32 v[66:67], v[66:67], v[224:225]
	v_rcp_f32_e32 v224, v1
	v_and_b32_e32 v1, 0xffff0000, v226
	v_mul_f32_e32 v1, 0xbfb8aa3b, v1
	v_exp_f32_e32 v1, v1
	v_pk_mul_f32 v[212:213], v[216:217], v[212:213] op_sel_hi:[0,1]
	v_lshlrev_b32_e32 v3, 16, v230
	v_pk_mul_f32 v[212:213], v[232:233], v[212:213]
	v_add_f32_e32 v1, 1.0, v1
	v_rcp_f32_e32 v225, v1
	v_lshlrev_b32_e32 v1, 16, v227
	v_mul_f32_e32 v1, 0xbfb8aa3b, v1
	v_exp_f32_e32 v1, v1
	v_mul_f32_e32 v3, 0xbfb8aa3b, v3
	v_pk_mul_f32 v[64:65], v[64:65], v[212:213]
	v_exp_f32_e32 v212, v3
	v_add_f32_e32 v1, 1.0, v1
	v_rcp_f32_e32 v228, v1
	v_and_b32_e32 v1, 0xffff0000, v227
	v_and_b32_e32 v3, 0xffff0000, v230
	v_mul_f32_e32 v1, 0xbfb8aa3b, v1
	v_mul_f32_e32 v3, 0xbfb8aa3b, v3
	v_exp_f32_e32 v1, v1
	v_exp_f32_e32 v213, v3
	v_lshlrev_b32_e32 v3, 16, v231
	v_mul_f32_e32 v3, 0xbfb8aa3b, v3
	v_exp_f32_e32 v226, v3
; DI float lo16(unsigned u) { return __uint_as_float(u << 16); }
; DI float hi16(unsigned u) { return __uint_as_float(u & 0xffff0000u); }
;     DI void mid(f32x4 (&acc)[2][2][4][2], const Unit& u, int wr, int wc, int fr, int fq) const {
;     ...
;             for (int m = 0; m < 4; ++m)
; #pragma unroll
;                 for (int bj = 0; bj < 2; ++bj) {
;                     const unsigned gsw[4] = {gs[m][bj].x, gs[m][bj].y, gs[m][bj].z, gs[m][bj].w}, gnw[4] = {gn[m][bj].x, gn[m][bj].y, gn[m][bj].z, gn[m][bj].w};
; #pragma unroll
;                     for (int j = 0; j < 4; ++j) {
;                         const float r0 = rs[m] * (1.f + __expf(-lo16(gnw[j]))) * __builtin_amdgcn_rcpf(1.f + __expf(-lo16(gsw[j])));
;                         const float r1 = rs[m] * (1.f + __expf(-hi16(gnw[j]))) * __builtin_amdgcn_rcpf(1.f + __expf(-hi16(gsw[j])));
;                         acc[ai][bj][m][j >> 1][(j & 1) * 2] *= r0; acc[ai][bj][m][j >> 1][(j & 1) * 2 + 1] *= r1; } }
	v_and_b32_e32 v3, 0xffff0000, v231
	v_mul_f32_e32 v3, 0xbfb8aa3b, v3
	v_add_f32_e32 v1, 1.0, v1
	v_exp_f32_e32 v227, v3
	v_rcp_f32_e32 v229, v1
	v_lshlrev_b32_e32 v1, 16, v184
	v_mul_f32_e32 v1, 0xbfb8aa3b, v1
	v_exp_f32_e32 v1, v1
	v_pk_add_f32 v[212:213], v[212:213], 1.0 op_sel_hi:[1,0]
	v_pk_add_f32 v[226:227], v[226:227], 1.0 op_sel_hi:[1,0]
	v_pk_mul_f32 v[212:213], v[216:217], v[212:213] op_sel_hi:[0,1]
	v_pk_mul_f32 v[226:227], v[216:217], v[226:227] op_sel_hi:[0,1]
	v_pk_mul_f32 v[212:213], v[224:225], v[212:213]
	v_pk_mul_f32 v[224:225], v[228:229], v[226:227]
	v_add_f32_e32 v1, 1.0, v1
	v_pk_mul_f32 v[62:63], v[62:63], v[224:225]
	v_rcp_f32_e32 v224, v1
	v_and_b32_e32 v1, 0xffff0000, v184
	v_mul_f32_e32 v1, 0xbfb8aa3b, v1
	v_exp_f32_e32 v1, v1
	v_lshlrev_b32_e32 v3, 16, v180
	v_mul_f32_e32 v3, 0xbfb8aa3b, v3
	v_pk_mul_f32 v[60:61], v[60:61], v[212:213]
	v_add_f32_e32 v1, 1.0, v1
	v_rcp_f32_e32 v225, v1
	v_lshlrev_b32_e32 v1, 16, v185
	v_mul_f32_e32 v1, 0xbfb8aa3b, v1
	v_exp_f32_e32 v1, v1
	v_exp_f32_e32 v212, v3
	v_and_b32_e32 v3, 0xffff0000, v180
	v_mul_f32_e32 v3, 0xbfb8aa3b, v3
	v_add_f32_e32 v1, 1.0, v1
	v_rcp_f32_e32 v184, v1
	v_and_b32_e32 v1, 0xffff0000, v185
	v_mul_f32_e32 v1, 0xbfb8aa3b, v1
	v_exp_f32_e32 v1, v1
	v_exp_f32_e32 v213, v3
	v_lshlrev_b32_e32 v3, 16, v181
	v_mul_f32_e32 v3, 0xbfb8aa3b, v3
	v_exp_f32_e32 v180, v3
	v_and_b32_e32 v3, 0xffff0000, v181
	v_add_f32_e32 v1, 1.0, v1
	v_mul_f32_e32 v3, 0xbfb8aa3b, v3
	v_rcp_f32_e32 v185, v1
	v_lshlrev_b32_e32 v1, 16, v186
	v_exp_f32_e32 v181, v3
	v_mul_f32_e32 v1, 0xbfb8aa3b, v1
	v_exp_f32_e32 v1, v1
	v_lshlrev_b32_e32 v3, 16, v182
	v_pk_add_f32 v[180:181], v[180:181], 1.0 op_sel_hi:[1,0]
	v_mul_f32_e32 v3, 0xbfb8aa3b, v3
	v_pk_mul_f32 v[180:181], v[216:217], v[180:181] op_sel_hi:[0,1]
	v_add_f32_e32 v1, 1.0, v1
	v_pk_mul_f32 v[180:181], v[184:185], v[180:181]
	v_rcp_f32_e32 v184, v1
	v_and_b32_e32 v1, 0xffff0000, v186
	v_mul_f32_e32 v1, 0xbfb8aa3b, v1
	v_exp_f32_e32 v1, v1
	v_pk_mul_f32 v[58:59], v[58:59], v[180:181]
	v_exp_f32_e32 v180, v3
	v_and_b32_e32 v3, 0xffff0000, v182
	v_add_f32_e32 v1, 1.0, v1
	v_rcp_f32_e32 v185, v1
	v_lshlrev_b32_e32 v1, 16, v187
	v_mul_f32_e32 v1, 0xbfb8aa3b, v1
	v_exp_f32_e32 v1, v1
	v_mul_f32_e32 v3, 0xbfb8aa3b, v3
	v_exp_f32_e32 v181, v3
	v_lshlrev_b32_e32 v3, 16, v183
	v_add_f32_e32 v1, 1.0, v1
	v_rcp_f32_e32 v186, v1
	v_and_b32_e32 v1, 0xffff0000, v187
	v_mul_f32_e32 v1, 0xbfb8aa3b, v1
	v_exp_f32_e32 v1, v1
	v_mul_f32_e32 v3, 0xbfb8aa3b, v3
	v_exp_f32_e32 v182, v3
	v_and_b32_e32 v3, 0xffff0000, v183
	v_mul_f32_e32 v3, 0xbfb8aa3b, v3
	v_add_f32_e32 v1, 1.0, v1
	v_exp_f32_e32 v183, v3
	v_rcp_f32_e32 v187, v1
	v_lshlrev_b32_e32 v1, 16, v172
	v_mul_f32_e32 v1, 0xbfb8aa3b, v1
	v_exp_f32_e32 v1, v1
	v_pk_add_f32 v[182:183], v[182:183], 1.0 op_sel_hi:[1,0]
	v_pk_add_f32 v[180:181], v[180:181], 1.0 op_sel_hi:[1,0]
	v_pk_mul_f32 v[182:183], v[216:217], v[182:183] op_sel_hi:[0,1]
	v_pk_mul_f32 v[182:183], v[186:187], v[182:183]
	v_add_f32_e32 v1, 1.0, v1
	v_pk_mul_f32 v[54:55], v[54:55], v[182:183]
	v_rcp_f32_e32 v182, v1
	v_and_b32_e32 v1, 0xffff0000, v172
	v_mul_f32_e32 v1, 0xbfb8aa3b, v1
	v_exp_f32_e32 v1, v1
	v_pk_mul_f32 v[180:181], v[216:217], v[180:181] op_sel_hi:[0,1]
	v_lshlrev_b32_e32 v3, 16, v176
	v_pk_mul_f32 v[180:181], v[184:185], v[180:181]
	v_add_f32_e32 v1, 1.0, v1
	v_rcp_f32_e32 v183, v1
	v_lshlrev_b32_e32 v1, 16, v173
	v_mul_f32_e32 v1, 0xbfb8aa3b, v1
	v_exp_f32_e32 v1, v1
	v_mul_f32_e32 v3, 0xbfb8aa3b, v3
	v_pk_mul_f32 v[52:53], v[52:53], v[180:181]
	v_exp_f32_e32 v180, v3
	v_add_f32_e32 v1, 1.0, v1
	v_and_b32_e32 v3, 0xffff0000, v176
	v_rcp_f32_e32 v176, v1
	v_and_b32_e32 v1, 0xffff0000, v173
	v_mul_f32_e32 v1, 0xbfb8aa3b, v1
	v_exp_f32_e32 v1, v1
	v_mul_f32_e32 v3, 0xbfb8aa3b, v3
	v_exp_f32_e32 v181, v3
	v_lshlrev_b32_e32 v3, 16, v177
	v_mul_f32_e32 v3, 0xbfb8aa3b, v3
	v_exp_f32_e32 v172, v3
	v_and_b32_e32 v3, 0xffff0000, v177
	v_add_f32_e32 v1, 1.0, v1
	v_mul_f32_e32 v3, 0xbfb8aa3b, v3
	v_rcp_f32_e32 v177, v1
	v_lshlrev_b32_e32 v1, 16, v174
	v_exp_f32_e32 v173, v3
	v_mul_f32_e32 v1, 0xbfb8aa3b, v1
	v_exp_f32_e32 v1, v1
	v_lshlrev_b32_e32 v3, 16, v178
	v_pk_add_f32 v[172:173], v[172:173], 1.0 op_sel_hi:[1,0]
	v_mul_f32_e32 v3, 0xbfb8aa3b, v3
	s_waitcnt vmcnt(0)
; DI float lo16(unsigned u) { return __uint_as_float(u << 16); }
; DI float hi16(unsigned u) { return __uint_as_float(u & 0xffff0000u); }
;     DI void mid(f32x4 (&acc)[2][2][4][2], const Unit& u, int wr, int wc, int fr, int fq) const {
;     ...
;             for (int m = 0; m < 4; ++m) { const int row = row0 + ai * HALF + m * 16; const bf16_t* rowp = P + (size_t)row * LDP + col0; rs[m] = rstd[row];
; #pragma unroll
;                 for (int bj = 0; bj < 2; ++bj) { gs[m][bj] = *(const u32x4*)(rowp + bj * HALF + C_GLS); gn[m][bj] = *(const u32x4*)(rowp + bj * HALF + C_GLN); } }
; #pragma unroll
;             for (int m = 0; m < 4; ++m)
; #pragma unroll
;                 for (int bj = 0; bj < 2; ++bj) {
;                     const unsigned gsw[4] = {gs[m][bj].x, gs[m][bj].y, gs[m][bj].z, gs[m][bj].w}, gnw[4] = {gn[m][bj].x, gn[m][bj].y, gn[m][bj].z, gn[m][bj].w};
; #pragma unroll
;                     for (int j = 0; j < 4; ++j) {
;                         const float r0 = rs[m] * (1.f + __expf(-lo16(gnw[j]))) * __builtin_amdgcn_rcpf(1.f + __expf(-lo16(gsw[j])));
;                         const float r1 = rs[m] * (1.f + __expf(-hi16(gnw[j]))) * __builtin_amdgcn_rcpf(1.f + __expf(-hi16(gsw[j])));
;                         acc[ai][bj][m][j >> 1][(j & 1) * 2] *= r0; acc[ai][bj][m][j >> 1][(j & 1) * 2 + 1] *= r1; } }
	v_pk_mul_f32 v[172:173], v[214:215], v[172:173] op_sel_hi:[0,1]
	v_add_f32_e32 v1, 1.0, v1
	v_pk_mul_f32 v[172:173], v[176:177], v[172:173]
	v_rcp_f32_e32 v176, v1
	v_and_b32_e32 v1, 0xffff0000, v174
	v_mul_f32_e32 v1, 0xbfb8aa3b, v1
	v_exp_f32_e32 v1, v1
	v_pk_mul_f32 v[50:51], v[50:51], v[172:173]
	v_exp_f32_e32 v172, v3
	v_and_b32_e32 v3, 0xffff0000, v178
	v_add_f32_e32 v1, 1.0, v1
	v_rcp_f32_e32 v177, v1
	v_lshlrev_b32_e32 v1, 16, v175
	v_mul_f32_e32 v1, 0xbfb8aa3b, v1
	v_exp_f32_e32 v1, v1
	v_mul_f32_e32 v3, 0xbfb8aa3b, v3
	v_exp_f32_e32 v173, v3
	v_lshlrev_b32_e32 v3, 16, v179
	v_add_f32_e32 v1, 1.0, v1
	v_rcp_f32_e32 v178, v1
	v_and_b32_e32 v1, 0xffff0000, v175
	v_mul_f32_e32 v1, 0xbfb8aa3b, v1
	v_exp_f32_e32 v1, v1
	v_mul_f32_e32 v3, 0xbfb8aa3b, v3
	v_exp_f32_e32 v174, v3
	v_and_b32_e32 v3, 0xffff0000, v179
	v_mul_f32_e32 v3, 0xbfb8aa3b, v3
	v_add_f32_e32 v1, 1.0, v1
	v_exp_f32_e32 v175, v3
	v_rcp_f32_e32 v179, v1
	v_lshlrev_b32_e32 v1, 16, v168
	v_mul_f32_e32 v1, 0xbfb8aa3b, v1
	v_exp_f32_e32 v1, v1
	v_pk_add_f32 v[174:175], v[174:175], 1.0 op_sel_hi:[1,0]
	v_pk_add_f32 v[172:173], v[172:173], 1.0 op_sel_hi:[1,0]
	v_pk_mul_f32 v[174:175], v[214:215], v[174:175] op_sel_hi:[0,1]
	v_pk_mul_f32 v[174:175], v[178:179], v[174:175]
	v_add_f32_e32 v1, 1.0, v1
	v_pk_mul_f32 v[46:47], v[46:47], v[174:175]
	v_rcp_f32_e32 v174, v1
	v_and_b32_e32 v1, 0xffff0000, v168
	v_mul_f32_e32 v1, 0xbfb8aa3b, v1
	v_exp_f32_e32 v1, v1
	v_pk_mul_f32 v[172:173], v[214:215], v[172:173] op_sel_hi:[0,1]
	v_lshlrev_b32_e32 v3, 16, v164
	v_pk_mul_f32 v[172:173], v[176:177], v[172:173]
	v_add_f32_e32 v1, 1.0, v1
	v_rcp_f32_e32 v175, v1
	v_lshlrev_b32_e32 v1, 16, v169
	v_mul_f32_e32 v1, 0xbfb8aa3b, v1
	v_exp_f32_e32 v1, v1
	v_mul_f32_e32 v3, 0xbfb8aa3b, v3
	v_pk_mul_f32 v[44:45], v[44:45], v[172:173]
	v_exp_f32_e32 v172, v3
	v_add_f32_e32 v1, 1.0, v1
	v_rcp_f32_e32 v168, v1
	v_and_b32_e32 v1, 0xffff0000, v169
	v_mul_f32_e32 v1, 0xbfb8aa3b, v1
	v_and_b32_e32 v3, 0xffff0000, v164
	v_exp_f32_e32 v1, v1
	v_mul_f32_e32 v3, 0xbfb8aa3b, v3
	v_exp_f32_e32 v173, v3
	v_lshlrev_b32_e32 v3, 16, v165
	v_mul_f32_e32 v3, 0xbfb8aa3b, v3
	v_exp_f32_e32 v164, v3
	v_and_b32_e32 v3, 0xffff0000, v165
	v_add_f32_e32 v1, 1.0, v1
	v_mul_f32_e32 v3, 0xbfb8aa3b, v3
	v_rcp_f32_e32 v169, v1
	v_lshlrev_b32_e32 v1, 16, v170
	v_exp_f32_e32 v165, v3
	v_mul_f32_e32 v1, 0xbfb8aa3b, v1
	v_exp_f32_e32 v1, v1
	v_lshlrev_b32_e32 v3, 16, v166
	v_pk_add_f32 v[164:165], v[164:165], 1.0 op_sel_hi:[1,0]
	v_mul_f32_e32 v3, 0xbfb8aa3b, v3
	v_pk_mul_f32 v[164:165], v[214:215], v[164:165] op_sel_hi:[0,1]
	v_add_f32_e32 v1, 1.0, v1
	v_pk_mul_f32 v[164:165], v[168:169], v[164:165]
	v_rcp_f32_e32 v168, v1
	v_and_b32_e32 v1, 0xffff0000, v170
	v_mul_f32_e32 v1, 0xbfb8aa3b, v1
	v_exp_f32_e32 v1, v1
	v_pk_mul_f32 v[42:43], v[42:43], v[164:165]
	v_exp_f32_e32 v164, v3
	v_and_b32_e32 v3, 0xffff0000, v166
	v_add_f32_e32 v1, 1.0, v1
	v_rcp_f32_e32 v169, v1
	v_lshlrev_b32_e32 v1, 16, v171
	v_mul_f32_e32 v1, 0xbfb8aa3b, v1
	v_exp_f32_e32 v1, v1
	v_mul_f32_e32 v3, 0xbfb8aa3b, v3
	v_exp_f32_e32 v165, v3
	v_lshlrev_b32_e32 v3, 16, v167
	v_add_f32_e32 v1, 1.0, v1
	v_rcp_f32_e32 v170, v1
	v_and_b32_e32 v1, 0xffff0000, v171
	v_mul_f32_e32 v1, 0xbfb8aa3b, v1
	v_exp_f32_e32 v1, v1
	v_mul_f32_e32 v3, 0xbfb8aa3b, v3
	v_exp_f32_e32 v166, v3
	v_and_b32_e32 v3, 0xffff0000, v167
	v_mul_f32_e32 v3, 0xbfb8aa3b, v3
	v_add_f32_e32 v1, 1.0, v1
	v_exp_f32_e32 v167, v3
	v_rcp_f32_e32 v171, v1
	v_lshlrev_b32_e32 v1, 16, v156
	v_mul_f32_e32 v1, 0xbfb8aa3b, v1
	v_exp_f32_e32 v1, v1
	v_pk_add_f32 v[166:167], v[166:167], 1.0 op_sel_hi:[1,0]
	v_pk_add_f32 v[164:165], v[164:165], 1.0 op_sel_hi:[1,0]
	v_pk_mul_f32 v[166:167], v[214:215], v[166:167] op_sel_hi:[0,1]
	v_pk_mul_f32 v[166:167], v[170:171], v[166:167]
	v_add_f32_e32 v1, 1.0, v1
	v_pk_mul_f32 v[38:39], v[38:39], v[166:167]
	v_rcp_f32_e32 v166, v1
	v_and_b32_e32 v1, 0xffff0000, v156
	v_mul_f32_e32 v1, 0xbfb8aa3b, v1
	v_exp_f32_e32 v1, v1
	v_pk_mul_f32 v[164:165], v[214:215], v[164:165] op_sel_hi:[0,1]
	v_lshlrev_b32_e32 v3, 16, v160
	v_pk_mul_f32 v[164:165], v[168:169], v[164:165]
	v_add_f32_e32 v1, 1.0, v1
	v_rcp_f32_e32 v167, v1
	v_lshlrev_b32_e32 v1, 16, v157
	v_mul_f32_e32 v1, 0xbfb8aa3b, v1
	v_exp_f32_e32 v1, v1
	v_mul_f32_e32 v3, 0xbfb8aa3b, v3
	v_pk_mul_f32 v[36:37], v[36:37], v[164:165]
	v_exp_f32_e32 v164, v3
	v_add_f32_e32 v1, 1.0, v1
	v_and_b32_e32 v3, 0xffff0000, v160
	v_rcp_f32_e32 v160, v1
	v_and_b32_e32 v1, 0xffff0000, v157
	v_mul_f32_e32 v1, 0xbfb8aa3b, v1
	v_exp_f32_e32 v1, v1
	v_mul_f32_e32 v3, 0xbfb8aa3b, v3
	v_exp_f32_e32 v165, v3
	v_lshlrev_b32_e32 v3, 16, v161
	v_mul_f32_e32 v3, 0xbfb8aa3b, v3
	v_exp_f32_e32 v156, v3
	v_and_b32_e32 v3, 0xffff0000, v161
	v_add_f32_e32 v1, 1.0, v1
	v_mul_f32_e32 v3, 0xbfb8aa3b, v3
	v_rcp_f32_e32 v161, v1
	v_lshlrev_b32_e32 v1, 16, v158
	v_exp_f32_e32 v157, v3
	v_mul_f32_e32 v1, 0xbfb8aa3b, v1
	v_exp_f32_e32 v1, v1
	v_add_co_u32_e32 v134, vcc, s55, v132
	v_pk_add_f32 v[156:157], v[156:157], 1.0 op_sel_hi:[1,0]
	s_nop 0
	v_addc_co_u32_e32 v135, vcc, 0, v133, vcc
	v_add_co_u32_e32 v132, vcc, s49, v132
	v_pk_mul_f32 v[156:157], v[210:211], v[156:157] op_sel_hi:[0,1]
	s_nop 0
	v_addc_co_u32_e32 v133, vcc, 0, v133, vcc
	v_add_f32_e32 v1, 1.0, v1
	global_load_dwordx4 v[140:143], v[134:135], off offset:1024
	global_load_dwordx4 v[136:139], v[134:135], off offset:1280
	global_load_dwordx4 v[144:147], v[132:133], off offset:1024
	s_nop 0
	global_load_dwordx4 v[132:135], v[132:133], off offset:1280
	v_pk_mul_f32 v[156:157], v[160:161], v[156:157]
	v_rcp_f32_e32 v160, v1
	v_and_b32_e32 v1, 0xffff0000, v158
	v_mul_f32_e32 v1, 0xbfb8aa3b, v1
; DI float lo16(unsigned u) { return __uint_as_float(u << 16); }
; DI float hi16(unsigned u) { return __uint_as_float(u & 0xffff0000u); }
;     DI void mid(f32x4 (&acc)[2][2][4][2], const Unit& u, int wr, int wc, int fr, int fq) const {
;     ...
;             for (int m = 0; m < 4; ++m)
; #pragma unroll
;                 for (int bj = 0; bj < 2; ++bj) {
;                     const unsigned gsw[4] = {gs[m][bj].x, gs[m][bj].y, gs[m][bj].z, gs[m][bj].w}, gnw[4] = {gn[m][bj].x, gn[m][bj].y, gn[m][bj].z, gn[m][bj].w};
; #pragma unroll
;                     for (int j = 0; j < 4; ++j) {
;                         const float r0 = rs[m] * (1.f + __expf(-lo16(gnw[j]))) * __builtin_amdgcn_rcpf(1.f + __expf(-lo16(gsw[j])));
;                         const float r1 = rs[m] * (1.f + __expf(-hi16(gnw[j]))) * __builtin_amdgcn_rcpf(1.f + __expf(-hi16(gsw[j])));
;                         acc[ai][bj][m][j >> 1][(j & 1) * 2] *= r0; acc[ai][bj][m][j >> 1][(j & 1) * 2 + 1] *= r1; } }
	v_exp_f32_e32 v1, v1
	v_lshlrev_b32_e32 v3, 16, v162
	v_mul_f32_e32 v3, 0xbfb8aa3b, v3
	v_pk_mul_f32 v[34:35], v[34:35], v[156:157]
	v_add_f32_e32 v1, 1.0, v1
	v_rcp_f32_e32 v161, v1
	v_lshlrev_b32_e32 v1, 16, v159
	v_mul_f32_e32 v1, 0xbfb8aa3b, v1
	v_exp_f32_e32 v1, v1
	v_exp_f32_e32 v156, v3
	v_and_b32_e32 v3, 0xffff0000, v162
	v_mul_f32_e32 v3, 0xbfb8aa3b, v3
	v_add_f32_e32 v1, 1.0, v1
	v_rcp_f32_e32 v162, v1
	v_and_b32_e32 v1, 0xffff0000, v159
	v_mul_f32_e32 v1, 0xbfb8aa3b, v1
	v_exp_f32_e32 v1, v1
	v_exp_f32_e32 v157, v3
	v_lshlrev_b32_e32 v3, 16, v163
	v_mul_f32_e32 v3, 0xbfb8aa3b, v3
	v_exp_f32_e32 v158, v3
	v_and_b32_e32 v3, 0xffff0000, v163
	v_mul_f32_e32 v3, 0xbfb8aa3b, v3
	v_add_f32_e32 v1, 1.0, v1
	v_exp_f32_e32 v159, v3
	v_rcp_f32_e32 v163, v1
	v_lshlrev_b32_e32 v1, 16, v152
	v_mul_f32_e32 v1, 0xbfb8aa3b, v1
	v_exp_f32_e32 v1, v1
	v_pk_add_f32 v[158:159], v[158:159], 1.0 op_sel_hi:[1,0]
	v_pk_add_f32 v[156:157], v[156:157], 1.0 op_sel_hi:[1,0]
	v_pk_mul_f32 v[158:159], v[210:211], v[158:159] op_sel_hi:[0,1]
	v_pk_mul_f32 v[158:159], v[162:163], v[158:159]
	v_add_f32_e32 v1, 1.0, v1
	v_pk_mul_f32 v[30:31], v[30:31], v[158:159]
	v_rcp_f32_e32 v158, v1
	v_and_b32_e32 v1, 0xffff0000, v152
	v_mul_f32_e32 v1, 0xbfb8aa3b, v1
	v_exp_f32_e32 v1, v1
	v_pk_mul_f32 v[156:157], v[210:211], v[156:157] op_sel_hi:[0,1]
	v_lshlrev_b32_e32 v3, 16, v148
	v_pk_mul_f32 v[156:157], v[160:161], v[156:157]
	v_add_f32_e32 v1, 1.0, v1
	v_rcp_f32_e32 v159, v1
	v_lshlrev_b32_e32 v1, 16, v153
	v_mul_f32_e32 v1, 0xbfb8aa3b, v1
	v_exp_f32_e32 v1, v1
	v_mul_f32_e32 v3, 0xbfb8aa3b, v3
	v_pk_mul_f32 v[28:29], v[28:29], v[156:157]
	v_exp_f32_e32 v156, v3
	v_add_f32_e32 v1, 1.0, v1
	v_rcp_f32_e32 v152, v1
	v_and_b32_e32 v1, 0xffff0000, v153
	v_mul_f32_e32 v1, 0xbfb8aa3b, v1
	v_and_b32_e32 v3, 0xffff0000, v148
	v_exp_f32_e32 v1, v1
	v_mul_f32_e32 v3, 0xbfb8aa3b, v3
	v_exp_f32_e32 v157, v3
	v_lshlrev_b32_e32 v3, 16, v149
	v_mul_f32_e32 v3, 0xbfb8aa3b, v3
	v_exp_f32_e32 v148, v3
	v_and_b32_e32 v3, 0xffff0000, v149
	v_add_f32_e32 v1, 1.0, v1
	v_mul_f32_e32 v3, 0xbfb8aa3b, v3
	v_rcp_f32_e32 v153, v1
	v_lshlrev_b32_e32 v1, 16, v154
	v_exp_f32_e32 v149, v3
	v_mul_f32_e32 v1, 0xbfb8aa3b, v1
	v_exp_f32_e32 v1, v1
	v_lshlrev_b32_e32 v3, 16, v150
	v_pk_add_f32 v[148:149], v[148:149], 1.0 op_sel_hi:[1,0]
	v_mul_f32_e32 v3, 0xbfb8aa3b, v3
	v_pk_mul_f32 v[148:149], v[210:211], v[148:149] op_sel_hi:[0,1]
	v_add_f32_e32 v1, 1.0, v1
	v_pk_mul_f32 v[148:149], v[152:153], v[148:149]
	v_rcp_f32_e32 v152, v1
	v_and_b32_e32 v1, 0xffff0000, v154
	v_mul_f32_e32 v1, 0xbfb8aa3b, v1
	v_exp_f32_e32 v1, v1
	v_pk_mul_f32 v[26:27], v[26:27], v[148:149]
	v_exp_f32_e32 v148, v3
	v_and_b32_e32 v3, 0xffff0000, v150
	v_add_f32_e32 v1, 1.0, v1
	v_rcp_f32_e32 v153, v1
	v_lshlrev_b32_e32 v1, 16, v155
	v_mul_f32_e32 v1, 0xbfb8aa3b, v1
	v_exp_f32_e32 v1, v1
	v_mul_f32_e32 v3, 0xbfb8aa3b, v3
	v_exp_f32_e32 v149, v3
	v_lshlrev_b32_e32 v3, 16, v151
	v_add_f32_e32 v1, 1.0, v1
	v_rcp_f32_e32 v154, v1
	v_and_b32_e32 v1, 0xffff0000, v155
	v_mul_f32_e32 v1, 0xbfb8aa3b, v1
	v_exp_f32_e32 v1, v1
	v_mul_f32_e32 v3, 0xbfb8aa3b, v3
	v_exp_f32_e32 v150, v3
	v_and_b32_e32 v3, 0xffff0000, v151
	v_mul_f32_e32 v3, 0xbfb8aa3b, v3
	v_add_f32_e32 v1, 1.0, v1
	v_exp_f32_e32 v151, v3
	v_rcp_f32_e32 v155, v1
	s_waitcnt vmcnt(0)
; DI float lo16(unsigned u) { return __uint_as_float(u << 16); }
; DI float hi16(unsigned u) { return __uint_as_float(u & 0xffff0000u); }
; template <class Epi>
; DI void gemm_phase(LAS unsigned char* lds, const Gemm g, const StaticOrder& S, const Epi& E) {
;     ...
;             if constexpr (Epi::HAS_MID) { if (t == Epi::MID_T) E.mid(acc, cur, wr, wc, fr, fq); }
;     DI void mid(f32x4 (&acc)[2][2][4][2], const Unit& u, int wr, int wc, int fr, int fq) const {
;     ...
;             for (int m = 0; m < 4; ++m)
; #pragma unroll
;                 for (int bj = 0; bj < 2; ++bj) {
;                     const unsigned gsw[4] = {gs[m][bj].x, gs[m][bj].y, gs[m][bj].z, gs[m][bj].w}, gnw[4] = {gn[m][bj].x, gn[m][bj].y, gn[m][bj].z, gn[m][bj].w};
; #pragma unroll
;                     for (int j = 0; j < 4; ++j) {
;                         const float r0 = rs[m] * (1.f + __expf(-lo16(gnw[j]))) * __builtin_amdgcn_rcpf(1.f + __expf(-lo16(gsw[j])));
;                         const float r1 = rs[m] * (1.f + __expf(-hi16(gnw[j]))) * __builtin_amdgcn_rcpf(1.f + __expf(-hi16(gsw[j])));
;                         acc[ai][bj][m][j >> 1][(j & 1) * 2] *= r0; acc[ai][bj][m][j >> 1][(j & 1) * 2 + 1] *= r1; } }
;             asm volatile("" ::: "memory");
	v_lshlrev_b32_e32 v1, 16, v140
	v_mul_f32_e32 v1, 0xbfb8aa3b, v1
	v_exp_f32_e32 v1, v1
	v_pk_add_f32 v[150:151], v[150:151], 1.0 op_sel_hi:[1,0]
	v_pk_add_f32 v[148:149], v[148:149], 1.0 op_sel_hi:[1,0]
	v_pk_mul_f32 v[150:151], v[210:211], v[150:151] op_sel_hi:[0,1]
	v_pk_mul_f32 v[150:151], v[154:155], v[150:151]
	v_add_f32_e32 v1, 1.0, v1
	v_pk_mul_f32 v[22:23], v[22:23], v[150:151]
	v_rcp_f32_e32 v150, v1
	v_and_b32_e32 v1, 0xffff0000, v140
	v_mul_f32_e32 v1, 0xbfb8aa3b, v1
	v_exp_f32_e32 v1, v1
	v_pk_mul_f32 v[148:149], v[210:211], v[148:149] op_sel_hi:[0,1]
	v_lshlrev_b32_e32 v3, 16, v144
	v_pk_mul_f32 v[148:149], v[152:153], v[148:149]
	v_add_f32_e32 v1, 1.0, v1
	v_rcp_f32_e32 v151, v1
	v_lshlrev_b32_e32 v1, 16, v141
	v_mul_f32_e32 v1, 0xbfb8aa3b, v1
	v_exp_f32_e32 v1, v1
	v_mul_f32_e32 v3, 0xbfb8aa3b, v3
	v_pk_mul_f32 v[20:21], v[20:21], v[148:149]
	v_exp_f32_e32 v148, v3
	v_add_f32_e32 v1, 1.0, v1
	v_and_b32_e32 v3, 0xffff0000, v144
	v_rcp_f32_e32 v144, v1
	v_and_b32_e32 v1, 0xffff0000, v141
	v_mul_f32_e32 v1, 0xbfb8aa3b, v1
	v_exp_f32_e32 v1, v1
	v_mul_f32_e32 v3, 0xbfb8aa3b, v3
	v_exp_f32_e32 v149, v3
	v_lshlrev_b32_e32 v3, 16, v145
	v_mul_f32_e32 v3, 0xbfb8aa3b, v3
	v_exp_f32_e32 v140, v3
	v_and_b32_e32 v3, 0xffff0000, v145
	v_add_f32_e32 v1, 1.0, v1
	v_mul_f32_e32 v3, 0xbfb8aa3b, v3
	v_rcp_f32_e32 v145, v1
	v_lshlrev_b32_e32 v1, 16, v142
	v_exp_f32_e32 v141, v3
	v_mul_f32_e32 v1, 0xbfb8aa3b, v1
	v_exp_f32_e32 v1, v1
	v_pk_add_f32 v[148:149], v[148:149], 1.0 op_sel_hi:[1,0]
	v_pk_add_f32 v[140:141], v[140:141], 1.0 op_sel_hi:[1,0]
	v_pk_mul_f32 v[148:149], v[2:3], v[148:149] op_sel_hi:[0,1]
	v_pk_mul_f32 v[140:141], v[2:3], v[140:141] op_sel_hi:[0,1]
	v_add_f32_e32 v1, 1.0, v1
	v_pk_mul_f32 v[140:141], v[144:145], v[140:141]
	v_rcp_f32_e32 v144, v1
	v_and_b32_e32 v1, 0xffff0000, v142
	v_mul_f32_e32 v1, 0xbfb8aa3b, v1
	v_exp_f32_e32 v1, v1
	v_lshlrev_b32_e32 v3, 16, v146
	v_mul_f32_e32 v3, 0xbfb8aa3b, v3
	v_pk_mul_f32 v[18:19], v[18:19], v[140:141]
	v_add_f32_e32 v1, 1.0, v1
	v_rcp_f32_e32 v145, v1
	v_lshlrev_b32_e32 v1, 16, v143
	v_mul_f32_e32 v1, 0xbfb8aa3b, v1
	v_exp_f32_e32 v1, v1
	v_exp_f32_e32 v140, v3
	v_and_b32_e32 v3, 0xffff0000, v146
	v_mul_f32_e32 v3, 0xbfb8aa3b, v3
	v_add_f32_e32 v1, 1.0, v1
	v_rcp_f32_e32 v146, v1
	v_and_b32_e32 v1, 0xffff0000, v143
	v_mul_f32_e32 v1, 0xbfb8aa3b, v1
	v_exp_f32_e32 v1, v1
	v_exp_f32_e32 v141, v3
	v_lshlrev_b32_e32 v3, 16, v147
	v_mul_f32_e32 v3, 0xbfb8aa3b, v3
	v_exp_f32_e32 v142, v3
	v_and_b32_e32 v3, 0xffff0000, v147
	v_mul_f32_e32 v3, 0xbfb8aa3b, v3
	v_add_f32_e32 v1, 1.0, v1
	v_exp_f32_e32 v143, v3
	v_rcp_f32_e32 v147, v1
	v_lshlrev_b32_e32 v1, 16, v136
	v_mul_f32_e32 v1, 0xbfb8aa3b, v1
	v_exp_f32_e32 v1, v1
	v_pk_add_f32 v[142:143], v[142:143], 1.0 op_sel_hi:[1,0]
	v_pk_add_f32 v[140:141], v[140:141], 1.0 op_sel_hi:[1,0]
	v_pk_mul_f32 v[142:143], v[2:3], v[142:143] op_sel_hi:[0,1]
	v_pk_mul_f32 v[142:143], v[146:147], v[142:143]
	v_add_f32_e32 v1, 1.0, v1
	v_pk_mul_f32 v[14:15], v[14:15], v[142:143]
	v_rcp_f32_e32 v142, v1
	v_and_b32_e32 v1, 0xffff0000, v136
	v_mul_f32_e32 v1, 0xbfb8aa3b, v1
	v_exp_f32_e32 v1, v1
	v_pk_mul_f32 v[140:141], v[2:3], v[140:141] op_sel_hi:[0,1]
	v_lshlrev_b32_e32 v3, 16, v132
	v_pk_mul_f32 v[140:141], v[144:145], v[140:141]
	v_add_f32_e32 v1, 1.0, v1
	v_rcp_f32_e32 v143, v1
	v_lshlrev_b32_e32 v1, 16, v137
	v_mul_f32_e32 v1, 0xbfb8aa3b, v1
	v_exp_f32_e32 v1, v1
	v_mul_f32_e32 v3, 0xbfb8aa3b, v3
	v_pk_mul_f32 v[12:13], v[12:13], v[140:141]
	v_exp_f32_e32 v140, v3
	v_add_f32_e32 v1, 1.0, v1
	v_rcp_f32_e32 v136, v1
	v_and_b32_e32 v1, 0xffff0000, v137
	v_mul_f32_e32 v1, 0xbfb8aa3b, v1
	v_and_b32_e32 v3, 0xffff0000, v132
	v_exp_f32_e32 v1, v1
	v_mul_f32_e32 v3, 0xbfb8aa3b, v3
	v_exp_f32_e32 v141, v3
	v_lshlrev_b32_e32 v3, 16, v133
	v_mul_f32_e32 v3, 0xbfb8aa3b, v3
	v_exp_f32_e32 v132, v3
	v_and_b32_e32 v3, 0xffff0000, v133
	v_add_f32_e32 v1, 1.0, v1
	v_mul_f32_e32 v3, 0xbfb8aa3b, v3
	v_rcp_f32_e32 v137, v1
	v_lshlrev_b32_e32 v1, 16, v138
	v_exp_f32_e32 v133, v3
	v_mul_f32_e32 v1, 0xbfb8aa3b, v1
	v_exp_f32_e32 v1, v1
	v_pk_add_f32 v[140:141], v[140:141], 1.0 op_sel_hi:[1,0]
	v_pk_add_f32 v[132:133], v[132:133], 1.0 op_sel_hi:[1,0]
	v_pk_mul_f32 v[140:141], v[2:3], v[140:141] op_sel_hi:[0,1]
	v_pk_mul_f32 v[132:133], v[2:3], v[132:133] op_sel_hi:[0,1]
	v_add_f32_e32 v1, 1.0, v1
	v_pk_mul_f32 v[132:133], v[136:137], v[132:133]
	v_rcp_f32_e32 v136, v1
	v_and_b32_e32 v1, 0xffff0000, v138
	v_mul_f32_e32 v1, 0xbfb8aa3b, v1
	v_exp_f32_e32 v1, v1
	v_lshlrev_b32_e32 v3, 16, v134
	v_mul_f32_e32 v3, 0xbfb8aa3b, v3
	v_pk_mul_f32 v[10:11], v[10:11], v[132:133]
	v_add_f32_e32 v1, 1.0, v1
	v_rcp_f32_e32 v137, v1
	v_lshlrev_b32_e32 v1, 16, v139
	v_mul_f32_e32 v1, 0xbfb8aa3b, v1
	v_exp_f32_e32 v1, v1
	v_exp_f32_e32 v132, v3
	v_and_b32_e32 v3, 0xffff0000, v134
	v_mul_f32_e32 v3, 0xbfb8aa3b, v3
	v_add_f32_e32 v1, 1.0, v1
	v_rcp_f32_e32 v138, v1
	v_and_b32_e32 v1, 0xffff0000, v139
	v_exp_f32_e32 v133, v3
	v_lshlrev_b32_e32 v3, 16, v135
	v_mul_f32_e32 v1, 0xbfb8aa3b, v1
	v_mul_f32_e32 v3, 0xbfb8aa3b, v3
	v_exp_f32_e32 v1, v1
	v_exp_f32_e32 v134, v3
	v_and_b32_e32 v3, 0xffff0000, v135
	v_mul_f32_e32 v3, 0xbfb8aa3b, v3
	v_exp_f32_e32 v135, v3
	v_add_f32_e32 v1, 1.0, v1
	v_rcp_f32_e32 v139, v1
	v_pk_add_f32 v[212:213], v[212:213], 1.0 op_sel_hi:[1,0]
	v_pk_add_f32 v[180:181], v[180:181], 1.0 op_sel_hi:[1,0]
	v_pk_add_f32 v[172:173], v[172:173], 1.0 op_sel_hi:[1,0]
	v_pk_add_f32 v[164:165], v[164:165], 1.0 op_sel_hi:[1,0]
	v_pk_add_f32 v[156:157], v[156:157], 1.0 op_sel_hi:[1,0]
	v_pk_add_f32 v[132:133], v[132:133], 1.0 op_sel_hi:[1,0]
	v_pk_add_f32 v[134:135], v[134:135], 1.0 op_sel_hi:[1,0]
	v_pk_mul_f32 v[212:213], v[216:217], v[212:213] op_sel_hi:[0,1]
	v_pk_mul_f32 v[180:181], v[214:215], v[180:181] op_sel_hi:[0,1]
	v_pk_mul_f32 v[172:173], v[214:215], v[172:173] op_sel_hi:[0,1]
	v_pk_mul_f32 v[164:165], v[210:211], v[164:165] op_sel_hi:[0,1]
	v_pk_mul_f32 v[156:157], v[210:211], v[156:157] op_sel_hi:[0,1]
	v_pk_mul_f32 v[134:135], v[2:3], v[134:135] op_sel_hi:[0,1]
	v_pk_mul_f32 v[2:3], v[2:3], v[132:133] op_sel_hi:[0,1]
	v_pk_mul_f32 v[212:213], v[224:225], v[212:213]
	v_pk_mul_f32 v[180:181], v[182:183], v[180:181]
	v_pk_mul_f32 v[172:173], v[174:175], v[172:173]
	v_pk_mul_f32 v[164:165], v[166:167], v[164:165]
	v_pk_mul_f32 v[156:157], v[158:159], v[156:157]
	v_pk_mul_f32 v[148:149], v[150:151], v[148:149]
	v_pk_mul_f32 v[140:141], v[142:143], v[140:141]
	v_pk_mul_f32 v[2:3], v[136:137], v[2:3]
	v_pk_mul_f32 v[132:133], v[138:139], v[134:135]
	v_pk_mul_f32 v[56:57], v[56:57], v[212:213]
	v_pk_mul_f32 v[48:49], v[48:49], v[180:181]
	v_pk_mul_f32 v[40:41], v[40:41], v[172:173]
	v_pk_mul_f32 v[32:33], v[32:33], v[164:165]
	v_pk_mul_f32 v[24:25], v[24:25], v[156:157]
	v_pk_mul_f32 v[16:17], v[16:17], v[148:149]
	v_pk_mul_f32 v[8:9], v[8:9], v[140:141]
	v_pk_mul_f32 v[6:7], v[6:7], v[132:133]
	v_pk_mul_f32 v[4:5], v[4:5], v[2:3]
	s_cmpk_le_u32 s42, 0xff
	s_cbranch_scc1 .Lhook_e1
	s_barrier
.Lhook_e1:
	s_branch .LBB0_630
